# write-through (sc1) result stores in G2/G3/G4 epilogues to shrink the L2 writeback at the phase barriers
# baseline (speedup 1.0000x reference)
.LBB0_815:
	s_and_b64 vcc, exec, s[28:29]
	s_cbranch_vccz .Lg2_epi_bf16
	v_lshl_add_u32 v238, s77, 8, v174
	v_lshl_or_b32 v237, s76, 8, v176
	v_lshl_add_u32 v237, v238, 10, v237
	v_lshlrev_b32_e32 v236, 2, v237
	v_lshlrev_b32_e32 v237, 1, v237
	v_lshlrev_b32_e32 v238, 2, v238
	global_load_dwordx4 v[132:135], v236, s[6:7]
	global_load_dwordx4 v[136:139], v236, s[6:7] offset:16
	global_load_dwordx4 v[148:151], v236, s[6:7] offset:512
	global_load_dwordx4 v[152:155], v236, s[6:7] offset:528
	v_add_u32_e32 v236, 0x10000, v236
	global_load_dwordx4 v[178:181], v236, s[6:7]
	global_load_dwordx4 v[182:185], v236, s[6:7] offset:16
	global_load_dwordx4 v[186:189], v236, s[6:7] offset:512
	global_load_dwordx4 v[190:193], v236, s[6:7] offset:528
	v_add_u32_e32 v236, 0x10000, v236
	global_load_dwordx4 v[200:203], v236, s[6:7]
	global_load_dwordx4 v[204:207], v236, s[6:7] offset:16
	global_load_dwordx4 v[208:211], v236, s[6:7] offset:512
	global_load_dwordx4 v[212:215], v236, s[6:7] offset:528
	v_add_u32_e32 v236, 0x10000, v236
	global_load_dwordx4 v[216:219], v236, s[6:7]
	global_load_dwordx4 v[220:223], v236, s[6:7] offset:16
	global_load_dwordx4 v[224:227], v236, s[6:7] offset:512
	global_load_dwordx4 v[228:231], v236, s[6:7] offset:528
	v_add_u32_e32 v236, 0x50000, v236
	v_xor_b32_e32 v239, 16, v197
	v_xor_b32_e32 v172, 32, v197
	v_lshlrev_b32_e32 v239, 2, v239
	v_lshlrev_b32_e32 v172, 2, v172
	s_waitcnt vmcnt(12)
	v_pk_add_f32 v[128:129], v[128:129], v[132:133]
	v_pk_add_f32 v[130:131], v[130:131], v[134:135]
	v_pk_add_f32 v[124:125], v[124:125], v[136:137]
	v_pk_add_f32 v[126:127], v[126:127], v[138:139]
	v_cvt_pk_bf16_f32 v132, v128, v129
	v_cvt_pk_bf16_f32 v133, v130, v131
	v_cvt_pk_bf16_f32 v134, v124, v125
	v_cvt_pk_bf16_f32 v135, v126, v127
	global_store_dwordx4 v237, v[132:135], s[8:9] sc1
	v_pk_mul_f32 v[128:129], v[128:129], v[128:129]
	v_pk_mul_f32 v[130:131], v[130:131], v[130:131]
	v_pk_fma_f32 v[128:129], v[124:125], v[124:125], v[128:129]
	v_pk_fma_f32 v[130:131], v[126:127], v[126:127], v[130:131]
	v_pk_add_f32 v[120:121], v[120:121], v[148:149]
	v_pk_add_f32 v[122:123], v[122:123], v[150:151]
	v_pk_add_f32 v[116:117], v[116:117], v[152:153]
	v_pk_add_f32 v[118:119], v[118:119], v[154:155]
	v_cvt_pk_bf16_f32 v148, v120, v121
	v_cvt_pk_bf16_f32 v149, v122, v123
	v_cvt_pk_bf16_f32 v150, v116, v117
	v_cvt_pk_bf16_f32 v151, v118, v119
	global_store_dwordx4 v237, v[148:151], s[8:9] offset:256 sc1
	v_pk_fma_f32 v[128:129], v[120:121], v[120:121], v[128:129]
	v_pk_fma_f32 v[130:131], v[122:123], v[122:123], v[130:131]
	v_pk_fma_f32 v[128:129], v[116:117], v[116:117], v[128:129]
	v_pk_fma_f32 v[130:131], v[118:119], v[118:119], v[130:131]
	v_add_u32_e32 v237, 0x8000, v237
	v_add_f32_e32 v128, v128, v129
	v_add_f32_e32 v130, v130, v131
	v_add_f32_e32 v128, v128, v130
	global_load_dwordx4 v[132:135], v236, s[6:7]
	global_load_dwordx4 v[136:139], v236, s[6:7] offset:16
	global_load_dwordx4 v[148:151], v236, s[6:7] offset:512
	global_load_dwordx4 v[152:155], v236, s[6:7] offset:528
	v_add_u32_e32 v236, 0x10000, v236
	s_waitcnt vmcnt(14)
	v_pk_add_f32 v[112:113], v[112:113], v[178:179]
	v_pk_add_f32 v[114:115], v[114:115], v[180:181]
	v_pk_add_f32 v[108:109], v[108:109], v[182:183]
	v_pk_add_f32 v[110:111], v[110:111], v[184:185]
	v_cvt_pk_bf16_f32 v178, v112, v113
	v_cvt_pk_bf16_f32 v179, v114, v115
	v_cvt_pk_bf16_f32 v180, v108, v109
	v_cvt_pk_bf16_f32 v181, v110, v111
	global_store_dwordx4 v237, v[178:181], s[8:9] sc1
	v_pk_mul_f32 v[112:113], v[112:113], v[112:113]
	v_pk_mul_f32 v[114:115], v[114:115], v[114:115]
	v_pk_fma_f32 v[112:113], v[108:109], v[108:109], v[112:113]
	v_pk_fma_f32 v[114:115], v[110:111], v[110:111], v[114:115]
	v_pk_add_f32 v[104:105], v[104:105], v[186:187]
	v_pk_add_f32 v[106:107], v[106:107], v[188:189]
	v_pk_add_f32 v[100:101], v[100:101], v[190:191]
	v_pk_add_f32 v[102:103], v[102:103], v[192:193]
	v_cvt_pk_bf16_f32 v186, v104, v105
	v_cvt_pk_bf16_f32 v187, v106, v107
	v_cvt_pk_bf16_f32 v188, v100, v101
	v_cvt_pk_bf16_f32 v189, v102, v103
	global_store_dwordx4 v237, v[186:189], s[8:9] offset:256 sc1
	v_pk_fma_f32 v[112:113], v[104:105], v[104:105], v[112:113]
	v_pk_fma_f32 v[114:115], v[106:107], v[106:107], v[114:115]
	v_pk_fma_f32 v[112:113], v[100:101], v[100:101], v[112:113]
	v_pk_fma_f32 v[114:115], v[102:103], v[102:103], v[114:115]
	v_add_u32_e32 v237, 0x8000, v237
	v_add_f32_e32 v112, v112, v113
	v_add_f32_e32 v114, v114, v115
	v_add_f32_e32 v112, v112, v114
	global_load_dwordx4 v[178:181], v236, s[6:7]
	global_load_dwordx4 v[182:185], v236, s[6:7] offset:16
	global_load_dwordx4 v[186:189], v236, s[6:7] offset:512
	global_load_dwordx4 v[190:193], v236, s[6:7] offset:528
	v_add_u32_e32 v236, 0x10000, v236
	s_waitcnt vmcnt(16)
	v_pk_add_f32 v[96:97], v[96:97], v[200:201]
	v_pk_add_f32 v[98:99], v[98:99], v[202:203]
	v_pk_add_f32 v[92:93], v[92:93], v[204:205]
	v_pk_add_f32 v[94:95], v[94:95], v[206:207]
	v_cvt_pk_bf16_f32 v200, v96, v97
	v_cvt_pk_bf16_f32 v201, v98, v99
	v_cvt_pk_bf16_f32 v202, v92, v93
	v_cvt_pk_bf16_f32 v203, v94, v95
	global_store_dwordx4 v237, v[200:203], s[8:9] sc1
	v_pk_mul_f32 v[96:97], v[96:97], v[96:97]
	v_pk_mul_f32 v[98:99], v[98:99], v[98:99]
	v_pk_fma_f32 v[96:97], v[92:93], v[92:93], v[96:97]
	v_pk_fma_f32 v[98:99], v[94:95], v[94:95], v[98:99]
	v_pk_add_f32 v[88:89], v[88:89], v[208:209]
	v_pk_add_f32 v[90:91], v[90:91], v[210:211]
	v_pk_add_f32 v[84:85], v[84:85], v[212:213]
	v_pk_add_f32 v[86:87], v[86:87], v[214:215]
	v_cvt_pk_bf16_f32 v208, v88, v89
	v_cvt_pk_bf16_f32 v209, v90, v91
	v_cvt_pk_bf16_f32 v210, v84, v85
	v_cvt_pk_bf16_f32 v211, v86, v87
	global_store_dwordx4 v237, v[208:211], s[8:9] offset:256 sc1
	v_pk_fma_f32 v[96:97], v[88:89], v[88:89], v[96:97]
	v_pk_fma_f32 v[98:99], v[90:91], v[90:91], v[98:99]
	v_pk_fma_f32 v[96:97], v[84:85], v[84:85], v[96:97]
	v_pk_fma_f32 v[98:99], v[86:87], v[86:87], v[98:99]
	v_add_u32_e32 v237, 0x8000, v237
	v_add_f32_e32 v96, v96, v97
	v_add_f32_e32 v98, v98, v99
	v_add_f32_e32 v96, v96, v98
	global_load_dwordx4 v[200:203], v236, s[6:7]
	global_load_dwordx4 v[204:207], v236, s[6:7] offset:16
	global_load_dwordx4 v[208:211], v236, s[6:7] offset:512
	global_load_dwordx4 v[212:215], v236, s[6:7] offset:528
	v_add_u32_e32 v236, 0x10000, v236
	s_waitcnt vmcnt(18)
	v_pk_add_f32 v[80:81], v[80:81], v[216:217]
	v_pk_add_f32 v[82:83], v[82:83], v[218:219]
	v_pk_add_f32 v[76:77], v[76:77], v[220:221]
	v_pk_add_f32 v[78:79], v[78:79], v[222:223]
	v_cvt_pk_bf16_f32 v216, v80, v81
	v_cvt_pk_bf16_f32 v217, v82, v83
	v_cvt_pk_bf16_f32 v218, v76, v77
	v_cvt_pk_bf16_f32 v219, v78, v79
	global_store_dwordx4 v237, v[216:219], s[8:9] sc1
	v_pk_mul_f32 v[80:81], v[80:81], v[80:81]
	v_pk_mul_f32 v[82:83], v[82:83], v[82:83]
	v_pk_fma_f32 v[80:81], v[76:77], v[76:77], v[80:81]
	v_pk_fma_f32 v[82:83], v[78:79], v[78:79], v[82:83]
	v_pk_add_f32 v[72:73], v[72:73], v[224:225]
	v_pk_add_f32 v[74:75], v[74:75], v[226:227]
	v_pk_add_f32 v[68:69], v[68:69], v[228:229]
	v_pk_add_f32 v[70:71], v[70:71], v[230:231]
	v_cvt_pk_bf16_f32 v224, v72, v73
	v_cvt_pk_bf16_f32 v225, v74, v75
	v_cvt_pk_bf16_f32 v226, v68, v69
	v_cvt_pk_bf16_f32 v227, v70, v71
	global_store_dwordx4 v237, v[224:227], s[8:9] offset:256 sc1
	v_pk_fma_f32 v[80:81], v[72:73], v[72:73], v[80:81]
	v_pk_fma_f32 v[82:83], v[74:75], v[74:75], v[82:83]
	v_pk_fma_f32 v[80:81], v[68:69], v[68:69], v[80:81]
	v_pk_fma_f32 v[82:83], v[70:71], v[70:71], v[82:83]
	v_add_u32_e32 v237, 0x28000, v237
	v_add_f32_e32 v80, v80, v81
	v_add_f32_e32 v82, v82, v83
	v_add_f32_e32 v80, v80, v82
	global_load_dwordx4 v[216:219], v236, s[6:7]
	global_load_dwordx4 v[220:223], v236, s[6:7] offset:16
	global_load_dwordx4 v[224:227], v236, s[6:7] offset:512
	global_load_dwordx4 v[228:231], v236, s[6:7] offset:528
	s_waitcnt vmcnt(18)
	v_pk_add_f32 v[64:65], v[64:65], v[132:133]
	v_pk_add_f32 v[66:67], v[66:67], v[134:135]
	v_pk_add_f32 v[60:61], v[60:61], v[136:137]
	v_pk_add_f32 v[62:63], v[62:63], v[138:139]
	v_cvt_pk_bf16_f32 v132, v64, v65
	v_cvt_pk_bf16_f32 v133, v66, v67
	v_cvt_pk_bf16_f32 v134, v60, v61
	v_cvt_pk_bf16_f32 v135, v62, v63
	global_store_dwordx4 v237, v[132:135], s[8:9] sc1
	v_pk_mul_f32 v[64:65], v[64:65], v[64:65]
	v_pk_mul_f32 v[66:67], v[66:67], v[66:67]
	v_pk_fma_f32 v[64:65], v[60:61], v[60:61], v[64:65]
	v_pk_fma_f32 v[66:67], v[62:63], v[62:63], v[66:67]
	v_pk_add_f32 v[56:57], v[56:57], v[148:149]
	v_pk_add_f32 v[58:59], v[58:59], v[150:151]
	v_pk_add_f32 v[52:53], v[52:53], v[152:153]
	v_pk_add_f32 v[54:55], v[54:55], v[154:155]
	v_cvt_pk_bf16_f32 v148, v56, v57
	v_cvt_pk_bf16_f32 v149, v58, v59
	v_cvt_pk_bf16_f32 v150, v52, v53
	v_cvt_pk_bf16_f32 v151, v54, v55
	global_store_dwordx4 v237, v[148:151], s[8:9] offset:256 sc1
	v_pk_fma_f32 v[64:65], v[56:57], v[56:57], v[64:65]
	v_pk_fma_f32 v[66:67], v[58:59], v[58:59], v[66:67]
	v_pk_fma_f32 v[64:65], v[52:53], v[52:53], v[64:65]
	v_pk_fma_f32 v[66:67], v[54:55], v[54:55], v[66:67]
	v_add_u32_e32 v237, 0x8000, v237
	v_add_f32_e32 v64, v64, v65
	v_add_f32_e32 v66, v66, v67
	v_add_f32_e32 v64, v64, v66
	s_waitcnt vmcnt(14)
	v_pk_add_f32 v[48:49], v[48:49], v[178:179]
	v_pk_add_f32 v[50:51], v[50:51], v[180:181]
	v_pk_add_f32 v[44:45], v[44:45], v[182:183]
	v_pk_add_f32 v[46:47], v[46:47], v[184:185]
	v_cvt_pk_bf16_f32 v178, v48, v49
	v_cvt_pk_bf16_f32 v179, v50, v51
	v_cvt_pk_bf16_f32 v180, v44, v45
	v_cvt_pk_bf16_f32 v181, v46, v47
	global_store_dwordx4 v237, v[178:181], s[8:9] sc1
	v_pk_mul_f32 v[48:49], v[48:49], v[48:49]
	v_pk_mul_f32 v[50:51], v[50:51], v[50:51]
	v_pk_fma_f32 v[48:49], v[44:45], v[44:45], v[48:49]
	v_pk_fma_f32 v[50:51], v[46:47], v[46:47], v[50:51]
	v_pk_add_f32 v[40:41], v[40:41], v[186:187]
	v_pk_add_f32 v[42:43], v[42:43], v[188:189]
	v_pk_add_f32 v[36:37], v[36:37], v[190:191]
	v_pk_add_f32 v[38:39], v[38:39], v[192:193]
	v_cvt_pk_bf16_f32 v186, v40, v41
	v_cvt_pk_bf16_f32 v187, v42, v43
	v_cvt_pk_bf16_f32 v188, v36, v37
	v_cvt_pk_bf16_f32 v189, v38, v39
	global_store_dwordx4 v237, v[186:189], s[8:9] offset:256 sc1
	v_pk_fma_f32 v[48:49], v[40:41], v[40:41], v[48:49]
	v_pk_fma_f32 v[50:51], v[42:43], v[42:43], v[50:51]
	v_pk_fma_f32 v[48:49], v[36:37], v[36:37], v[48:49]
	v_pk_fma_f32 v[50:51], v[38:39], v[38:39], v[50:51]
	v_add_u32_e32 v237, 0x8000, v237
	v_add_f32_e32 v48, v48, v49
	v_add_f32_e32 v50, v50, v51
	v_add_f32_e32 v48, v48, v50
	s_waitcnt vmcnt(10)
	v_pk_add_f32 v[32:33], v[32:33], v[200:201]
	v_pk_add_f32 v[34:35], v[34:35], v[202:203]
	v_pk_add_f32 v[28:29], v[28:29], v[204:205]
	v_pk_add_f32 v[30:31], v[30:31], v[206:207]
	v_cvt_pk_bf16_f32 v200, v32, v33
	v_cvt_pk_bf16_f32 v201, v34, v35
	v_cvt_pk_bf16_f32 v202, v28, v29
	v_cvt_pk_bf16_f32 v203, v30, v31
	global_store_dwordx4 v237, v[200:203], s[8:9] sc1
	v_pk_mul_f32 v[32:33], v[32:33], v[32:33]
	v_pk_mul_f32 v[34:35], v[34:35], v[34:35]
	v_pk_fma_f32 v[32:33], v[28:29], v[28:29], v[32:33]
	v_pk_fma_f32 v[34:35], v[30:31], v[30:31], v[34:35]
	v_pk_add_f32 v[24:25], v[24:25], v[208:209]
	v_pk_add_f32 v[26:27], v[26:27], v[210:211]
	v_pk_add_f32 v[20:21], v[20:21], v[212:213]
	v_pk_add_f32 v[22:23], v[22:23], v[214:215]
	v_cvt_pk_bf16_f32 v208, v24, v25
	v_cvt_pk_bf16_f32 v209, v26, v27
	v_cvt_pk_bf16_f32 v210, v20, v21
	v_cvt_pk_bf16_f32 v211, v22, v23
	global_store_dwordx4 v237, v[208:211], s[8:9] offset:256 sc1
	v_pk_fma_f32 v[32:33], v[24:25], v[24:25], v[32:33]
	v_pk_fma_f32 v[34:35], v[26:27], v[26:27], v[34:35]
	v_pk_fma_f32 v[32:33], v[20:21], v[20:21], v[32:33]
	v_pk_fma_f32 v[34:35], v[22:23], v[22:23], v[34:35]
	v_add_u32_e32 v237, 0x8000, v237
	v_add_f32_e32 v32, v32, v33
	v_add_f32_e32 v34, v34, v35
	v_add_f32_e32 v32, v32, v34
	s_waitcnt vmcnt(6)
	v_pk_add_f32 v[16:17], v[16:17], v[216:217]
	v_pk_add_f32 v[18:19], v[18:19], v[218:219]
	v_pk_add_f32 v[12:13], v[12:13], v[220:221]
	v_pk_add_f32 v[14:15], v[14:15], v[222:223]
	v_cvt_pk_bf16_f32 v216, v16, v17
	v_cvt_pk_bf16_f32 v217, v18, v19
	v_cvt_pk_bf16_f32 v218, v12, v13
	v_cvt_pk_bf16_f32 v219, v14, v15
	global_store_dwordx4 v237, v[216:219], s[8:9] sc1
	v_pk_mul_f32 v[16:17], v[16:17], v[16:17]
	v_pk_mul_f32 v[18:19], v[18:19], v[18:19]
	v_pk_fma_f32 v[16:17], v[12:13], v[12:13], v[16:17]
	v_pk_fma_f32 v[18:19], v[14:15], v[14:15], v[18:19]
	v_pk_add_f32 v[8:9], v[8:9], v[224:225]
	v_pk_add_f32 v[10:11], v[10:11], v[226:227]
	v_pk_add_f32 v[4:5], v[4:5], v[228:229]
	v_pk_add_f32 v[6:7], v[6:7], v[230:231]
	v_cvt_pk_bf16_f32 v224, v8, v9
	v_cvt_pk_bf16_f32 v225, v10, v11
	v_cvt_pk_bf16_f32 v226, v4, v5
	v_cvt_pk_bf16_f32 v227, v6, v7
	global_store_dwordx4 v237, v[224:227], s[8:9] offset:256 sc1
	v_pk_fma_f32 v[16:17], v[8:9], v[8:9], v[16:17]
	v_pk_fma_f32 v[18:19], v[10:11], v[10:11], v[18:19]
	v_pk_fma_f32 v[16:17], v[4:5], v[4:5], v[16:17]
	v_pk_fma_f32 v[18:19], v[6:7], v[6:7], v[18:19]
	v_add_f32_e32 v16, v16, v17
	v_add_f32_e32 v18, v18, v19
	v_add_f32_e32 v16, v16, v18
	ds_bpermute_b32 v129, v239, v128
	ds_bpermute_b32 v113, v239, v112
	ds_bpermute_b32 v97, v239, v96
	ds_bpermute_b32 v81, v239, v80
	ds_bpermute_b32 v65, v239, v64
	ds_bpermute_b32 v49, v239, v48
	ds_bpermute_b32 v33, v239, v32
	ds_bpermute_b32 v17, v239, v16
	s_waitcnt lgkmcnt(0)
	v_add_f32_e32 v128, v128, v129
	v_add_f32_e32 v112, v112, v113
	v_add_f32_e32 v96, v96, v97
	v_add_f32_e32 v80, v80, v81
	v_add_f32_e32 v64, v64, v65
	v_add_f32_e32 v48, v48, v49
	v_add_f32_e32 v32, v32, v33
	v_add_f32_e32 v16, v16, v17
	ds_bpermute_b32 v129, v172, v128
	ds_bpermute_b32 v113, v172, v112
	ds_bpermute_b32 v97, v172, v96
	ds_bpermute_b32 v81, v172, v80
	ds_bpermute_b32 v65, v172, v64
	ds_bpermute_b32 v49, v172, v48
	ds_bpermute_b32 v33, v172, v32
	ds_bpermute_b32 v17, v172, v16
	s_waitcnt lgkmcnt(0)
	s_and_saveexec_b64 s[14:15], s[0:1]
	v_add_f32_e32 v128, v128, v129
	v_add_f32_e32 v112, v112, v113
	v_add_f32_e32 v96, v96, v97
	v_add_f32_e32 v80, v80, v81
	v_add_f32_e32 v64, v64, v65
	v_add_f32_e32 v48, v48, v49
	v_add_f32_e32 v32, v32, v33
	v_add_f32_e32 v16, v16, v17
	global_atomic_add_f32 v238, v128, s[10:11]
	global_atomic_add_f32 v238, v112, s[10:11] offset:64
	global_atomic_add_f32 v238, v96, s[10:11] offset:128
	global_atomic_add_f32 v238, v80, s[10:11] offset:192
	global_atomic_add_f32 v238, v64, s[10:11] offset:512
	global_atomic_add_f32 v238, v48, s[10:11] offset:576
	global_atomic_add_f32 v238, v32, s[10:11] offset:640
	global_atomic_add_f32 v238, v16, s[10:11] offset:704
	s_branch .LBB0_879
.Lg2_epi_bf16:
	v_lshl_add_u32 v238, s77, 8, v174
	v_lshl_or_b32 v237, s76, 8, v176
	v_lshl_add_u32 v236, v238, 10, v237
	v_lshlrev_b32_e32 v236, 1, v236
	v_mov_b32_e32 v237, v236
	v_lshlrev_b32_e32 v238, 2, v238
	global_load_dwordx4 v[132:135], v236, s[8:9]
	global_load_dwordx4 v[136:139], v236, s[8:9] offset:256
	v_add_u32_e32 v236, 0x8000, v236
	global_load_dwordx4 v[148:151], v236, s[8:9]
	global_load_dwordx4 v[152:155], v236, s[8:9] offset:256
	v_add_u32_e32 v236, 0x8000, v236
	global_load_dwordx4 v[178:181], v236, s[8:9]
	global_load_dwordx4 v[182:185], v236, s[8:9] offset:256
	v_add_u32_e32 v236, 0x8000, v236
	global_load_dwordx4 v[186:189], v236, s[8:9]
	global_load_dwordx4 v[190:193], v236, s[8:9] offset:256
	v_add_u32_e32 v236, 0x28000, v236
	global_load_dwordx4 v[200:203], v236, s[8:9]
	global_load_dwordx4 v[204:207], v236, s[8:9] offset:256
	v_add_u32_e32 v236, 0x8000, v236
	global_load_dwordx4 v[208:211], v236, s[8:9]
	global_load_dwordx4 v[212:215], v236, s[8:9] offset:256
	v_add_u32_e32 v236, 0x8000, v236
	global_load_dwordx4 v[216:219], v236, s[8:9]
	global_load_dwordx4 v[220:223], v236, s[8:9] offset:256
	v_add_u32_e32 v236, 0x8000, v236
	global_load_dwordx4 v[224:227], v236, s[8:9]
	global_load_dwordx4 v[228:231], v236, s[8:9] offset:256
	v_xor_b32_e32 v239, 16, v197
	v_xor_b32_e32 v172, 32, v197
	v_lshlrev_b32_e32 v239, 2, v239
	v_lshlrev_b32_e32 v172, 2, v172
	s_waitcnt vmcnt(14)
	v_lshlrev_b32_e32 v232, 16, v132
	v_and_b32_e32 v233, 0xffff0000, v132
	v_lshlrev_b32_e32 v234, 16, v133
	v_and_b32_e32 v235, 0xffff0000, v133
	v_lshlrev_b32_e32 v132, 16, v134
	v_and_b32_e32 v133, 0xffff0000, v134
	v_lshlrev_b32_e32 v134, 16, v135
	v_and_b32_e32 v135, 0xffff0000, v135
	v_pk_add_f32 v[128:129], v[128:129], v[232:233]
	v_pk_add_f32 v[130:131], v[130:131], v[234:235]
	v_pk_add_f32 v[124:125], v[124:125], v[132:133]
	v_pk_add_f32 v[126:127], v[126:127], v[134:135]
	v_cvt_pk_bf16_f32 v132, v128, v129
	v_cvt_pk_bf16_f32 v133, v130, v131
	v_cvt_pk_bf16_f32 v134, v124, v125
	v_cvt_pk_bf16_f32 v135, v126, v127
	global_store_dwordx4 v237, v[132:135], s[8:9] sc1
	v_pk_mul_f32 v[128:129], v[128:129], v[128:129]
	v_pk_mul_f32 v[130:131], v[130:131], v[130:131]
	v_pk_fma_f32 v[128:129], v[124:125], v[124:125], v[128:129]
	v_pk_fma_f32 v[130:131], v[126:127], v[126:127], v[130:131]
	v_lshlrev_b32_e32 v232, 16, v136
	v_and_b32_e32 v233, 0xffff0000, v136
	v_lshlrev_b32_e32 v234, 16, v137
	v_and_b32_e32 v235, 0xffff0000, v137
	v_lshlrev_b32_e32 v136, 16, v138
	v_and_b32_e32 v137, 0xffff0000, v138
	v_lshlrev_b32_e32 v138, 16, v139
	v_and_b32_e32 v139, 0xffff0000, v139
	v_pk_add_f32 v[120:121], v[120:121], v[232:233]
	v_pk_add_f32 v[122:123], v[122:123], v[234:235]
	v_pk_add_f32 v[116:117], v[116:117], v[136:137]
	v_pk_add_f32 v[118:119], v[118:119], v[138:139]
	v_cvt_pk_bf16_f32 v136, v120, v121
	v_cvt_pk_bf16_f32 v137, v122, v123
	v_cvt_pk_bf16_f32 v138, v116, v117
	v_cvt_pk_bf16_f32 v139, v118, v119
	global_store_dwordx4 v237, v[136:139], s[8:9] offset:256 sc1
	v_pk_fma_f32 v[128:129], v[120:121], v[120:121], v[128:129]
	v_pk_fma_f32 v[130:131], v[122:123], v[122:123], v[130:131]
	v_pk_fma_f32 v[128:129], v[116:117], v[116:117], v[128:129]
	v_pk_fma_f32 v[130:131], v[118:119], v[118:119], v[130:131]
	v_add_u32_e32 v237, 0x8000, v237
	v_add_f32_e32 v128, v128, v129
	v_add_f32_e32 v130, v130, v131
	v_add_f32_e32 v128, v128, v130
	s_waitcnt vmcnt(14)
	v_lshlrev_b32_e32 v232, 16, v148
	v_and_b32_e32 v233, 0xffff0000, v148
	v_lshlrev_b32_e32 v234, 16, v149
	v_and_b32_e32 v235, 0xffff0000, v149
	v_lshlrev_b32_e32 v148, 16, v150
	v_and_b32_e32 v149, 0xffff0000, v150
	v_lshlrev_b32_e32 v150, 16, v151
	v_and_b32_e32 v151, 0xffff0000, v151
	v_pk_add_f32 v[112:113], v[112:113], v[232:233]
	v_pk_add_f32 v[114:115], v[114:115], v[234:235]
	v_pk_add_f32 v[108:109], v[108:109], v[148:149]
	v_pk_add_f32 v[110:111], v[110:111], v[150:151]
	v_cvt_pk_bf16_f32 v148, v112, v113
	v_cvt_pk_bf16_f32 v149, v114, v115
	v_cvt_pk_bf16_f32 v150, v108, v109
	v_cvt_pk_bf16_f32 v151, v110, v111
	global_store_dwordx4 v237, v[148:151], s[8:9] sc1
	v_pk_mul_f32 v[112:113], v[112:113], v[112:113]
	v_pk_mul_f32 v[114:115], v[114:115], v[114:115]
	v_pk_fma_f32 v[112:113], v[108:109], v[108:109], v[112:113]
	v_pk_fma_f32 v[114:115], v[110:111], v[110:111], v[114:115]
	v_lshlrev_b32_e32 v232, 16, v152
	v_and_b32_e32 v233, 0xffff0000, v152
	v_lshlrev_b32_e32 v234, 16, v153
	v_and_b32_e32 v235, 0xffff0000, v153
	v_lshlrev_b32_e32 v152, 16, v154
	v_and_b32_e32 v153, 0xffff0000, v154
	v_lshlrev_b32_e32 v154, 16, v155
	v_and_b32_e32 v155, 0xffff0000, v155
	v_pk_add_f32 v[104:105], v[104:105], v[232:233]
	v_pk_add_f32 v[106:107], v[106:107], v[234:235]
	v_pk_add_f32 v[100:101], v[100:101], v[152:153]
	v_pk_add_f32 v[102:103], v[102:103], v[154:155]
	v_cvt_pk_bf16_f32 v152, v104, v105
	v_cvt_pk_bf16_f32 v153, v106, v107
	v_cvt_pk_bf16_f32 v154, v100, v101
	v_cvt_pk_bf16_f32 v155, v102, v103
	global_store_dwordx4 v237, v[152:155], s[8:9] offset:256 sc1
	v_pk_fma_f32 v[112:113], v[104:105], v[104:105], v[112:113]
	v_pk_fma_f32 v[114:115], v[106:107], v[106:107], v[114:115]
	v_pk_fma_f32 v[112:113], v[100:101], v[100:101], v[112:113]
	v_pk_fma_f32 v[114:115], v[102:103], v[102:103], v[114:115]
	v_add_u32_e32 v237, 0x8000, v237
	v_add_f32_e32 v112, v112, v113
	v_add_f32_e32 v114, v114, v115
	v_add_f32_e32 v112, v112, v114
	s_waitcnt vmcnt(14)
	v_lshlrev_b32_e32 v232, 16, v178
	v_and_b32_e32 v233, 0xffff0000, v178
	v_lshlrev_b32_e32 v234, 16, v179
	v_and_b32_e32 v235, 0xffff0000, v179
	v_lshlrev_b32_e32 v178, 16, v180
	v_and_b32_e32 v179, 0xffff0000, v180
	v_lshlrev_b32_e32 v180, 16, v181
	v_and_b32_e32 v181, 0xffff0000, v181
	v_pk_add_f32 v[96:97], v[96:97], v[232:233]
	v_pk_add_f32 v[98:99], v[98:99], v[234:235]
	v_pk_add_f32 v[92:93], v[92:93], v[178:179]
	v_pk_add_f32 v[94:95], v[94:95], v[180:181]
	v_cvt_pk_bf16_f32 v178, v96, v97
	v_cvt_pk_bf16_f32 v179, v98, v99
	v_cvt_pk_bf16_f32 v180, v92, v93
	v_cvt_pk_bf16_f32 v181, v94, v95
	global_store_dwordx4 v237, v[178:181], s[8:9] sc1
	v_pk_mul_f32 v[96:97], v[96:97], v[96:97]
	v_pk_mul_f32 v[98:99], v[98:99], v[98:99]
	v_pk_fma_f32 v[96:97], v[92:93], v[92:93], v[96:97]
	v_pk_fma_f32 v[98:99], v[94:95], v[94:95], v[98:99]
	v_lshlrev_b32_e32 v232, 16, v182
	v_and_b32_e32 v233, 0xffff0000, v182
	v_lshlrev_b32_e32 v234, 16, v183
	v_and_b32_e32 v235, 0xffff0000, v183
	v_lshlrev_b32_e32 v182, 16, v184
	v_and_b32_e32 v183, 0xffff0000, v184
	v_lshlrev_b32_e32 v184, 16, v185
	v_and_b32_e32 v185, 0xffff0000, v185
	v_pk_add_f32 v[88:89], v[88:89], v[232:233]
	v_pk_add_f32 v[90:91], v[90:91], v[234:235]
	v_pk_add_f32 v[84:85], v[84:85], v[182:183]
	v_pk_add_f32 v[86:87], v[86:87], v[184:185]
	v_cvt_pk_bf16_f32 v182, v88, v89
	v_cvt_pk_bf16_f32 v183, v90, v91
	v_cvt_pk_bf16_f32 v184, v84, v85
	v_cvt_pk_bf16_f32 v185, v86, v87
	global_store_dwordx4 v237, v[182:185], s[8:9] offset:256 sc1
	v_pk_fma_f32 v[96:97], v[88:89], v[88:89], v[96:97]
	v_pk_fma_f32 v[98:99], v[90:91], v[90:91], v[98:99]
	v_pk_fma_f32 v[96:97], v[84:85], v[84:85], v[96:97]
	v_pk_fma_f32 v[98:99], v[86:87], v[86:87], v[98:99]
	v_add_u32_e32 v237, 0x8000, v237
	v_add_f32_e32 v96, v96, v97
	v_add_f32_e32 v98, v98, v99
	v_add_f32_e32 v96, v96, v98
	s_waitcnt vmcnt(14)
	v_lshlrev_b32_e32 v232, 16, v186
	v_and_b32_e32 v233, 0xffff0000, v186
	v_lshlrev_b32_e32 v234, 16, v187
	v_and_b32_e32 v235, 0xffff0000, v187
	v_lshlrev_b32_e32 v186, 16, v188
	v_and_b32_e32 v187, 0xffff0000, v188
	v_lshlrev_b32_e32 v188, 16, v189
	v_and_b32_e32 v189, 0xffff0000, v189
	v_pk_add_f32 v[80:81], v[80:81], v[232:233]
	v_pk_add_f32 v[82:83], v[82:83], v[234:235]
	v_pk_add_f32 v[76:77], v[76:77], v[186:187]
	v_pk_add_f32 v[78:79], v[78:79], v[188:189]
	v_cvt_pk_bf16_f32 v186, v80, v81
	v_cvt_pk_bf16_f32 v187, v82, v83
	v_cvt_pk_bf16_f32 v188, v76, v77
	v_cvt_pk_bf16_f32 v189, v78, v79
	global_store_dwordx4 v237, v[186:189], s[8:9] sc1
	v_pk_mul_f32 v[80:81], v[80:81], v[80:81]
	v_pk_mul_f32 v[82:83], v[82:83], v[82:83]
	v_pk_fma_f32 v[80:81], v[76:77], v[76:77], v[80:81]
	v_pk_fma_f32 v[82:83], v[78:79], v[78:79], v[82:83]
	v_lshlrev_b32_e32 v232, 16, v190
	v_and_b32_e32 v233, 0xffff0000, v190
	v_lshlrev_b32_e32 v234, 16, v191
	v_and_b32_e32 v235, 0xffff0000, v191
	v_lshlrev_b32_e32 v190, 16, v192
	v_and_b32_e32 v191, 0xffff0000, v192
	v_lshlrev_b32_e32 v192, 16, v193
	v_and_b32_e32 v193, 0xffff0000, v193
	v_pk_add_f32 v[72:73], v[72:73], v[232:233]
	v_pk_add_f32 v[74:75], v[74:75], v[234:235]
	v_pk_add_f32 v[68:69], v[68:69], v[190:191]
	v_pk_add_f32 v[70:71], v[70:71], v[192:193]
	v_cvt_pk_bf16_f32 v190, v72, v73
	v_cvt_pk_bf16_f32 v191, v74, v75
	v_cvt_pk_bf16_f32 v192, v68, v69
	v_cvt_pk_bf16_f32 v193, v70, v71
	global_store_dwordx4 v237, v[190:193], s[8:9] offset:256 sc1
	v_pk_fma_f32 v[80:81], v[72:73], v[72:73], v[80:81]
	v_pk_fma_f32 v[82:83], v[74:75], v[74:75], v[82:83]
	v_pk_fma_f32 v[80:81], v[68:69], v[68:69], v[80:81]
	v_pk_fma_f32 v[82:83], v[70:71], v[70:71], v[82:83]
	v_add_u32_e32 v237, 0x28000, v237
	v_add_f32_e32 v80, v80, v81
	v_add_f32_e32 v82, v82, v83
	v_add_f32_e32 v80, v80, v82
	s_waitcnt vmcnt(14)
	v_lshlrev_b32_e32 v232, 16, v200
	v_and_b32_e32 v233, 0xffff0000, v200
	v_lshlrev_b32_e32 v234, 16, v201
	v_and_b32_e32 v235, 0xffff0000, v201
	v_lshlrev_b32_e32 v200, 16, v202
	v_and_b32_e32 v201, 0xffff0000, v202
	v_lshlrev_b32_e32 v202, 16, v203
	v_and_b32_e32 v203, 0xffff0000, v203
	v_pk_add_f32 v[64:65], v[64:65], v[232:233]
	v_pk_add_f32 v[66:67], v[66:67], v[234:235]
	v_pk_add_f32 v[60:61], v[60:61], v[200:201]
	v_pk_add_f32 v[62:63], v[62:63], v[202:203]
	v_cvt_pk_bf16_f32 v200, v64, v65
	v_cvt_pk_bf16_f32 v201, v66, v67
	v_cvt_pk_bf16_f32 v202, v60, v61
	v_cvt_pk_bf16_f32 v203, v62, v63
	global_store_dwordx4 v237, v[200:203], s[8:9] sc1
	v_pk_mul_f32 v[64:65], v[64:65], v[64:65]
	v_pk_mul_f32 v[66:67], v[66:67], v[66:67]
	v_pk_fma_f32 v[64:65], v[60:61], v[60:61], v[64:65]
	v_pk_fma_f32 v[66:67], v[62:63], v[62:63], v[66:67]
	v_lshlrev_b32_e32 v232, 16, v204
	v_and_b32_e32 v233, 0xffff0000, v204
	v_lshlrev_b32_e32 v234, 16, v205
	v_and_b32_e32 v235, 0xffff0000, v205
	v_lshlrev_b32_e32 v204, 16, v206
	v_and_b32_e32 v205, 0xffff0000, v206
	v_lshlrev_b32_e32 v206, 16, v207
	v_and_b32_e32 v207, 0xffff0000, v207
	v_pk_add_f32 v[56:57], v[56:57], v[232:233]
	v_pk_add_f32 v[58:59], v[58:59], v[234:235]
	v_pk_add_f32 v[52:53], v[52:53], v[204:205]
	v_pk_add_f32 v[54:55], v[54:55], v[206:207]
	v_cvt_pk_bf16_f32 v204, v56, v57
	v_cvt_pk_bf16_f32 v205, v58, v59
	v_cvt_pk_bf16_f32 v206, v52, v53
	v_cvt_pk_bf16_f32 v207, v54, v55
	global_store_dwordx4 v237, v[204:207], s[8:9] offset:256 sc1
	v_pk_fma_f32 v[64:65], v[56:57], v[56:57], v[64:65]
	v_pk_fma_f32 v[66:67], v[58:59], v[58:59], v[66:67]
	v_pk_fma_f32 v[64:65], v[52:53], v[52:53], v[64:65]
	v_pk_fma_f32 v[66:67], v[54:55], v[54:55], v[66:67]
	v_add_u32_e32 v237, 0x8000, v237
	v_add_f32_e32 v64, v64, v65
	v_add_f32_e32 v66, v66, v67
	v_add_f32_e32 v64, v64, v66
	s_waitcnt vmcnt(14)
	v_lshlrev_b32_e32 v232, 16, v208
	v_and_b32_e32 v233, 0xffff0000, v208
	v_lshlrev_b32_e32 v234, 16, v209
	v_and_b32_e32 v235, 0xffff0000, v209
	v_lshlrev_b32_e32 v208, 16, v210
	v_and_b32_e32 v209, 0xffff0000, v210
	v_lshlrev_b32_e32 v210, 16, v211
	v_and_b32_e32 v211, 0xffff0000, v211
	v_pk_add_f32 v[48:49], v[48:49], v[232:233]
	v_pk_add_f32 v[50:51], v[50:51], v[234:235]
	v_pk_add_f32 v[44:45], v[44:45], v[208:209]
	v_pk_add_f32 v[46:47], v[46:47], v[210:211]
	v_cvt_pk_bf16_f32 v208, v48, v49
	v_cvt_pk_bf16_f32 v209, v50, v51
	v_cvt_pk_bf16_f32 v210, v44, v45
	v_cvt_pk_bf16_f32 v211, v46, v47
	global_store_dwordx4 v237, v[208:211], s[8:9] sc1
	v_pk_mul_f32 v[48:49], v[48:49], v[48:49]
	v_pk_mul_f32 v[50:51], v[50:51], v[50:51]
	v_pk_fma_f32 v[48:49], v[44:45], v[44:45], v[48:49]
	v_pk_fma_f32 v[50:51], v[46:47], v[46:47], v[50:51]
	v_lshlrev_b32_e32 v232, 16, v212
	v_and_b32_e32 v233, 0xffff0000, v212
	v_lshlrev_b32_e32 v234, 16, v213
	v_and_b32_e32 v235, 0xffff0000, v213
	v_lshlrev_b32_e32 v212, 16, v214
	v_and_b32_e32 v213, 0xffff0000, v214
	v_lshlrev_b32_e32 v214, 16, v215
	v_and_b32_e32 v215, 0xffff0000, v215
	v_pk_add_f32 v[40:41], v[40:41], v[232:233]
	v_pk_add_f32 v[42:43], v[42:43], v[234:235]
	v_pk_add_f32 v[36:37], v[36:37], v[212:213]
	v_pk_add_f32 v[38:39], v[38:39], v[214:215]
	v_cvt_pk_bf16_f32 v212, v40, v41
	v_cvt_pk_bf16_f32 v213, v42, v43
	v_cvt_pk_bf16_f32 v214, v36, v37
	v_cvt_pk_bf16_f32 v215, v38, v39
	global_store_dwordx4 v237, v[212:215], s[8:9] offset:256 sc1
	v_pk_fma_f32 v[48:49], v[40:41], v[40:41], v[48:49]
	v_pk_fma_f32 v[50:51], v[42:43], v[42:43], v[50:51]
	v_pk_fma_f32 v[48:49], v[36:37], v[36:37], v[48:49]
	v_pk_fma_f32 v[50:51], v[38:39], v[38:39], v[50:51]
	v_add_u32_e32 v237, 0x8000, v237
	v_add_f32_e32 v48, v48, v49
	v_add_f32_e32 v50, v50, v51
	v_add_f32_e32 v48, v48, v50
	s_waitcnt vmcnt(14)
	v_lshlrev_b32_e32 v232, 16, v216
	v_and_b32_e32 v233, 0xffff0000, v216
	v_lshlrev_b32_e32 v234, 16, v217
	v_and_b32_e32 v235, 0xffff0000, v217
	v_lshlrev_b32_e32 v216, 16, v218
	v_and_b32_e32 v217, 0xffff0000, v218
	v_lshlrev_b32_e32 v218, 16, v219
	v_and_b32_e32 v219, 0xffff0000, v219
	v_pk_add_f32 v[32:33], v[32:33], v[232:233]
	v_pk_add_f32 v[34:35], v[34:35], v[234:235]
	v_pk_add_f32 v[28:29], v[28:29], v[216:217]
	v_pk_add_f32 v[30:31], v[30:31], v[218:219]
	v_cvt_pk_bf16_f32 v216, v32, v33
	v_cvt_pk_bf16_f32 v217, v34, v35
	v_cvt_pk_bf16_f32 v218, v28, v29
	v_cvt_pk_bf16_f32 v219, v30, v31
	global_store_dwordx4 v237, v[216:219], s[8:9] sc1
	v_pk_mul_f32 v[32:33], v[32:33], v[32:33]
	v_pk_mul_f32 v[34:35], v[34:35], v[34:35]
	v_pk_fma_f32 v[32:33], v[28:29], v[28:29], v[32:33]
	v_pk_fma_f32 v[34:35], v[30:31], v[30:31], v[34:35]
	v_lshlrev_b32_e32 v232, 16, v220
	v_and_b32_e32 v233, 0xffff0000, v220
	v_lshlrev_b32_e32 v234, 16, v221
	v_and_b32_e32 v235, 0xffff0000, v221
	v_lshlrev_b32_e32 v220, 16, v222
	v_and_b32_e32 v221, 0xffff0000, v222
	v_lshlrev_b32_e32 v222, 16, v223
	v_and_b32_e32 v223, 0xffff0000, v223
	v_pk_add_f32 v[24:25], v[24:25], v[232:233]
	v_pk_add_f32 v[26:27], v[26:27], v[234:235]
	v_pk_add_f32 v[20:21], v[20:21], v[220:221]
	v_pk_add_f32 v[22:23], v[22:23], v[222:223]
	v_cvt_pk_bf16_f32 v220, v24, v25
	v_cvt_pk_bf16_f32 v221, v26, v27
	v_cvt_pk_bf16_f32 v222, v20, v21
	v_cvt_pk_bf16_f32 v223, v22, v23
	global_store_dwordx4 v237, v[220:223], s[8:9] offset:256 sc1
	v_pk_fma_f32 v[32:33], v[24:25], v[24:25], v[32:33]
	v_pk_fma_f32 v[34:35], v[26:27], v[26:27], v[34:35]
	v_pk_fma_f32 v[32:33], v[20:21], v[20:21], v[32:33]
	v_pk_fma_f32 v[34:35], v[22:23], v[22:23], v[34:35]
	v_add_u32_e32 v237, 0x8000, v237
	v_add_f32_e32 v32, v32, v33
	v_add_f32_e32 v34, v34, v35
	v_add_f32_e32 v32, v32, v34
	s_waitcnt vmcnt(14)
	v_lshlrev_b32_e32 v232, 16, v224
	v_and_b32_e32 v233, 0xffff0000, v224
	v_lshlrev_b32_e32 v234, 16, v225
	v_and_b32_e32 v235, 0xffff0000, v225
	v_lshlrev_b32_e32 v224, 16, v226
	v_and_b32_e32 v225, 0xffff0000, v226
	v_lshlrev_b32_e32 v226, 16, v227
	v_and_b32_e32 v227, 0xffff0000, v227
	v_pk_add_f32 v[16:17], v[16:17], v[232:233]
	v_pk_add_f32 v[18:19], v[18:19], v[234:235]
	v_pk_add_f32 v[12:13], v[12:13], v[224:225]
	v_pk_add_f32 v[14:15], v[14:15], v[226:227]
	v_cvt_pk_bf16_f32 v224, v16, v17
	v_cvt_pk_bf16_f32 v225, v18, v19
	v_cvt_pk_bf16_f32 v226, v12, v13
	v_cvt_pk_bf16_f32 v227, v14, v15
	global_store_dwordx4 v237, v[224:227], s[8:9] sc1
	v_pk_mul_f32 v[16:17], v[16:17], v[16:17]
	v_pk_mul_f32 v[18:19], v[18:19], v[18:19]
	v_pk_fma_f32 v[16:17], v[12:13], v[12:13], v[16:17]
	v_pk_fma_f32 v[18:19], v[14:15], v[14:15], v[18:19]
	v_lshlrev_b32_e32 v232, 16, v228
	v_and_b32_e32 v233, 0xffff0000, v228
	v_lshlrev_b32_e32 v234, 16, v229
	v_and_b32_e32 v235, 0xffff0000, v229
	v_lshlrev_b32_e32 v228, 16, v230
	v_and_b32_e32 v229, 0xffff0000, v230
	v_lshlrev_b32_e32 v230, 16, v231
	v_and_b32_e32 v231, 0xffff0000, v231
	v_pk_add_f32 v[8:9], v[8:9], v[232:233]
	v_pk_add_f32 v[10:11], v[10:11], v[234:235]
	v_pk_add_f32 v[4:5], v[4:5], v[228:229]
	v_pk_add_f32 v[6:7], v[6:7], v[230:231]
	v_cvt_pk_bf16_f32 v228, v8, v9
	v_cvt_pk_bf16_f32 v229, v10, v11
	v_cvt_pk_bf16_f32 v230, v4, v5
	v_cvt_pk_bf16_f32 v231, v6, v7
	global_store_dwordx4 v237, v[228:231], s[8:9] offset:256 sc1
	v_pk_fma_f32 v[16:17], v[8:9], v[8:9], v[16:17]
	v_pk_fma_f32 v[18:19], v[10:11], v[10:11], v[18:19]
	v_pk_fma_f32 v[16:17], v[4:5], v[4:5], v[16:17]
	v_pk_fma_f32 v[18:19], v[6:7], v[6:7], v[18:19]
	v_add_f32_e32 v16, v16, v17
	v_add_f32_e32 v18, v18, v19
	v_add_f32_e32 v16, v16, v18
	ds_bpermute_b32 v129, v239, v128
	ds_bpermute_b32 v113, v239, v112
	ds_bpermute_b32 v97, v239, v96
	ds_bpermute_b32 v81, v239, v80
	ds_bpermute_b32 v65, v239, v64
	ds_bpermute_b32 v49, v239, v48
	ds_bpermute_b32 v33, v239, v32
	ds_bpermute_b32 v17, v239, v16
	s_waitcnt lgkmcnt(0)
	v_add_f32_e32 v128, v128, v129
	v_add_f32_e32 v112, v112, v113
	v_add_f32_e32 v96, v96, v97
	v_add_f32_e32 v80, v80, v81
	v_add_f32_e32 v64, v64, v65
	v_add_f32_e32 v48, v48, v49
	v_add_f32_e32 v32, v32, v33
	v_add_f32_e32 v16, v16, v17
	ds_bpermute_b32 v129, v172, v128
	ds_bpermute_b32 v113, v172, v112
	ds_bpermute_b32 v97, v172, v96
	ds_bpermute_b32 v81, v172, v80
	ds_bpermute_b32 v65, v172, v64
	ds_bpermute_b32 v49, v172, v48
	ds_bpermute_b32 v33, v172, v32
	ds_bpermute_b32 v17, v172, v16
	s_waitcnt lgkmcnt(0)
	s_and_saveexec_b64 s[14:15], s[0:1]
	v_add_f32_e32 v128, v128, v129
	v_add_f32_e32 v112, v112, v113
	v_add_f32_e32 v96, v96, v97
	v_add_f32_e32 v80, v80, v81
	v_add_f32_e32 v64, v64, v65
	v_add_f32_e32 v48, v48, v49
	v_add_f32_e32 v32, v32, v33
	v_add_f32_e32 v16, v16, v17
	global_atomic_add_f32 v238, v128, s[10:11]
	global_atomic_add_f32 v238, v112, s[10:11] offset:64
	global_atomic_add_f32 v238, v96, s[10:11] offset:128
	global_atomic_add_f32 v238, v80, s[10:11] offset:192
	global_atomic_add_f32 v238, v64, s[10:11] offset:512
	global_atomic_add_f32 v238, v48, s[10:11] offset:576
	global_atomic_add_f32 v238, v32, s[10:11] offset:640
	global_atomic_add_f32 v238, v16, s[10:11] offset:704

.LBB0_963:
	v_lshl_add_u32 v140, s51, 8, v144
	v_ashrrev_i32_e32 v141, 31, v140
	v_lshl_add_u64 v[142:143], v[140:141], 2, s[6:7]
	global_load_dword v200, v[142:143], off
	global_load_dword v201, v[142:143], off offset:64
	global_load_dword v202, v[142:143], off offset:128
	global_load_dword v203, v[142:143], off offset:192
	global_load_dword v204, v[142:143], off offset:512
	global_load_dword v205, v[142:143], off offset:576
	global_load_dword v206, v[142:143], off offset:640
	global_load_dword v207, v[142:143], off offset:704
	v_pk_mul_f32 v[150:151], v[118:119], v[122:123]
	v_lshl_or_b32 v148, s50, 7, v146
	v_pk_mul_f32 v[152:153], v[116:117], v[120:121]
	v_mov_b64_e32 v[120:121], s[8:9]
	v_ashrrev_i32_e32 v149, 31, v148
	v_mad_i64_i32 v[154:155], s[14:15], v140, s53, v[120:121]
	v_pk_mul_f32 v[128:129], v[124:125], v[128:129]
	v_pk_mul_f32 v[130:131], v[126:127], v[130:131]
	v_pk_mul_f32 v[102:103], v[106:107], v[102:103]
	v_pk_mul_f32 v[100:101], v[104:105], v[100:101]
	v_pk_mul_f32 v[114:115], v[110:111], v[114:115]
	v_pk_mul_f32 v[112:113], v[108:109], v[112:113]
	v_pk_mul_f32 v[86:87], v[90:91], v[86:87]
	v_pk_mul_f32 v[84:85], v[88:89], v[84:85]
	v_pk_mul_f32 v[98:99], v[94:95], v[98:99]
	v_pk_mul_f32 v[96:97], v[92:93], v[96:97]
	v_pk_mul_f32 v[70:71], v[74:75], v[70:71]
	v_pk_mul_f32 v[68:69], v[72:73], v[68:69]
	v_pk_mul_f32 v[82:83], v[78:79], v[82:83]
	v_pk_mul_f32 v[80:81], v[76:77], v[80:81]
	v_pk_mul_f32 v[54:55], v[58:59], v[54:55]
	v_pk_mul_f32 v[52:53], v[56:57], v[52:53]
	v_pk_mul_f32 v[66:67], v[62:63], v[66:67]
	v_pk_mul_f32 v[64:65], v[60:61], v[64:65]
	v_pk_mul_f32 v[38:39], v[42:43], v[38:39]
	v_pk_mul_f32 v[36:37], v[40:41], v[36:37]
	v_pk_mul_f32 v[50:51], v[46:47], v[50:51]
	v_pk_mul_f32 v[48:49], v[44:45], v[48:49]
	v_pk_mul_f32 v[22:23], v[26:27], v[22:23]
	v_pk_mul_f32 v[20:21], v[24:25], v[20:21]
	v_pk_mul_f32 v[34:35], v[30:31], v[34:35]
	v_pk_mul_f32 v[32:33], v[28:29], v[32:33]
	v_pk_mul_f32 v[10:11], v[6:7], v[10:11]
	v_pk_mul_f32 v[8:9], v[4:5], v[8:9]
	v_pk_mul_f32 v[18:19], v[14:15], v[18:19]
	v_pk_mul_f32 v[16:17], v[12:13], v[16:17]
	s_andn2_b64 vcc, exec, s[0:1]
	s_mov_b64 s[0:1], -1
	s_waitcnt vmcnt(0)
	v_fmamk_f32 v122, v200, 0x3a800000, v195
	v_rsq_f32_e32 v141, v122
	v_lshlrev_b64 v[122:123], 1, v[148:149]
	v_lshl_add_u64 v[148:149], v[154:155], 0, v[122:123]
	v_mul_f32_e32 v154, 0xbfb8aa3b, v141
	v_pk_mul_f32 v[124:125], v[124:125], v[154:155] op_sel_hi:[1,0]
	v_pk_mul_f32 v[118:119], v[118:119], v[154:155] op_sel_hi:[1,0]
	v_pk_mul_f32 v[116:117], v[116:117], v[154:155] op_sel_hi:[1,0]
	v_pk_mul_f32 v[126:127], v[126:127], v[154:155] op_sel_hi:[1,0]
	v_exp_f32_e32 v124, v124
	v_exp_f32_e32 v125, v125
	v_exp_f32_e32 v116, v116
	v_exp_f32_e32 v118, v118
	v_exp_f32_e32 v119, v119
	v_exp_f32_e32 v117, v117
	v_exp_f32_e32 v126, v126
	v_exp_f32_e32 v127, v127
	v_pk_add_f32 v[124:125], v[124:125], 1.0 op_sel_hi:[1,0]
	v_pk_add_f32 v[118:119], v[118:119], 1.0 op_sel_hi:[1,0]
	v_pk_add_f32 v[116:117], v[116:117], 1.0 op_sel_hi:[1,0]
	v_pk_add_f32 v[126:127], v[126:127], 1.0 op_sel_hi:[1,0]
	v_rcp_f32_e32 v124, v124
	v_rcp_f32_e32 v125, v125
	v_rcp_f32_e32 v116, v116
	v_rcp_f32_e32 v117, v117
	v_rcp_f32_e32 v118, v118
	v_rcp_f32_e32 v119, v119
	v_rcp_f32_e32 v126, v126
	v_rcp_f32_e32 v127, v127
	v_mul_f32_e32 v172, v141, v141
	v_pk_mul_f32 v[124:125], v[172:173], v[124:125] op_sel_hi:[0,1]
	v_pk_mul_f32 v[116:117], v[172:173], v[116:117] op_sel_hi:[0,1]
	v_pk_mul_f32 v[118:119], v[172:173], v[118:119] op_sel_hi:[0,1]
	v_pk_mul_f32 v[126:127], v[172:173], v[126:127] op_sel_hi:[0,1]
	v_pk_mul_f32 v[124:125], v[128:129], v[124:125]
	v_pk_mul_f32 v[128:129], v[150:151], v[118:119]
	v_pk_mul_f32 v[118:119], v[152:153], v[116:117]
	v_pk_mul_f32 v[126:127], v[130:131], v[126:127]
	v_cvt_pk_bf16_f32 v116, v124, v125
	s_nop 0
	v_cvt_pk_bf16_f32 v117, v126, v127
	v_cvt_pk_bf16_f32 v118, v118, v119
	v_cvt_pk_bf16_f32 v119, v128, v129
	global_store_dwordx4 v[148:149], v[116:119], off sc1
	s_nop 0
	s_nop 0
	v_or_b32_e32 v117, 16, v140
	v_fmamk_f32 v116, v201, 0x3a800000, v195
	v_rsq_f32_e32 v119, v116
	v_mad_i64_i32 v[116:117], s[14:15], v117, s53, v[120:121]
	v_lshl_add_u64 v[116:117], v[116:117], 0, v[122:123]
	v_mul_f32_e32 v118, 0xbfb8aa3b, v119
	v_pk_mul_f32 v[106:107], v[106:107], v[118:119] op_sel_hi:[1,0]
	v_pk_mul_f32 v[104:105], v[104:105], v[118:119] op_sel_hi:[1,0]
	v_pk_mul_f32 v[110:111], v[110:111], v[118:119] op_sel_hi:[1,0]
	v_pk_mul_f32 v[108:109], v[108:109], v[118:119] op_sel_hi:[1,0]
	v_exp_f32_e32 v104, v104
	v_exp_f32_e32 v106, v106
	v_exp_f32_e32 v107, v107
	v_exp_f32_e32 v105, v105
	v_exp_f32_e32 v108, v108
	v_exp_f32_e32 v109, v109
	v_exp_f32_e32 v110, v110
	v_exp_f32_e32 v111, v111
	v_pk_add_f32 v[106:107], v[106:107], 1.0 op_sel_hi:[1,0]
	v_pk_add_f32 v[104:105], v[104:105], 1.0 op_sel_hi:[1,0]
	v_pk_add_f32 v[108:109], v[108:109], 1.0 op_sel_hi:[1,0]
	v_pk_add_f32 v[110:111], v[110:111], 1.0 op_sel_hi:[1,0]
	v_rcp_f32_e32 v104, v104
	v_rcp_f32_e32 v105, v105
	v_rcp_f32_e32 v106, v106
	v_rcp_f32_e32 v107, v107
	v_rcp_f32_e32 v108, v108
	v_rcp_f32_e32 v109, v109
	v_rcp_f32_e32 v110, v110
	v_rcp_f32_e32 v111, v111
	v_mul_f32_e32 v124, v119, v119
	v_pk_mul_f32 v[104:105], v[124:125], v[104:105] op_sel_hi:[0,1]
	v_pk_mul_f32 v[106:107], v[124:125], v[106:107] op_sel_hi:[0,1]
	v_pk_mul_f32 v[108:109], v[124:125], v[108:109] op_sel_hi:[0,1]
	v_pk_mul_f32 v[110:111], v[124:125], v[110:111] op_sel_hi:[0,1]
	v_pk_mul_f32 v[106:107], v[102:103], v[106:107]
	v_pk_mul_f32 v[102:103], v[100:101], v[104:105]
	v_pk_mul_f32 v[110:111], v[114:115], v[110:111]
	v_pk_mul_f32 v[108:109], v[112:113], v[108:109]
	s_nop 0
	v_cvt_pk_bf16_f32 v100, v108, v109
	v_cvt_pk_bf16_f32 v101, v110, v111
	v_cvt_pk_bf16_f32 v102, v102, v103
	v_cvt_pk_bf16_f32 v103, v106, v107
	global_store_dwordx4 v[116:117], v[100:103], off sc1
	s_nop 0
	s_nop 0
	v_or_b32_e32 v101, 32, v140
	v_fmamk_f32 v100, v202, 0x3a800000, v195
	v_rsq_f32_e32 v103, v100
	v_mad_i64_i32 v[100:101], s[14:15], v101, s53, v[120:121]
	v_lshl_add_u64 v[100:101], v[100:101], 0, v[122:123]
	v_mul_f32_e32 v102, 0xbfb8aa3b, v103
	v_pk_mul_f32 v[90:91], v[90:91], v[102:103] op_sel_hi:[1,0]
	v_pk_mul_f32 v[88:89], v[88:89], v[102:103] op_sel_hi:[1,0]
	v_pk_mul_f32 v[94:95], v[94:95], v[102:103] op_sel_hi:[1,0]
	v_pk_mul_f32 v[92:93], v[92:93], v[102:103] op_sel_hi:[1,0]
	v_exp_f32_e32 v88, v88
	v_exp_f32_e32 v90, v90
	v_exp_f32_e32 v91, v91
	v_exp_f32_e32 v89, v89
	v_exp_f32_e32 v92, v92
	v_exp_f32_e32 v93, v93
	v_exp_f32_e32 v94, v94
	v_exp_f32_e32 v95, v95
	v_pk_add_f32 v[90:91], v[90:91], 1.0 op_sel_hi:[1,0]
	v_pk_add_f32 v[88:89], v[88:89], 1.0 op_sel_hi:[1,0]
	v_pk_add_f32 v[92:93], v[92:93], 1.0 op_sel_hi:[1,0]
	v_pk_add_f32 v[94:95], v[94:95], 1.0 op_sel_hi:[1,0]
	v_rcp_f32_e32 v88, v88
	v_rcp_f32_e32 v89, v89
	v_rcp_f32_e32 v90, v90
	v_rcp_f32_e32 v91, v91
	v_rcp_f32_e32 v92, v92
	v_rcp_f32_e32 v93, v93
	v_rcp_f32_e32 v94, v94
	v_rcp_f32_e32 v95, v95
	v_mul_f32_e32 v104, v103, v103
	v_pk_mul_f32 v[88:89], v[104:105], v[88:89] op_sel_hi:[0,1]
	v_pk_mul_f32 v[90:91], v[104:105], v[90:91] op_sel_hi:[0,1]
	v_pk_mul_f32 v[92:93], v[104:105], v[92:93] op_sel_hi:[0,1]
	v_pk_mul_f32 v[94:95], v[104:105], v[94:95] op_sel_hi:[0,1]
	v_pk_mul_f32 v[90:91], v[86:87], v[90:91]
	v_pk_mul_f32 v[86:87], v[84:85], v[88:89]
	v_pk_mul_f32 v[94:95], v[98:99], v[94:95]
	v_pk_mul_f32 v[92:93], v[96:97], v[92:93]
	s_nop 0
	v_cvt_pk_bf16_f32 v84, v92, v93
	v_cvt_pk_bf16_f32 v85, v94, v95
	v_cvt_pk_bf16_f32 v86, v86, v87
	v_cvt_pk_bf16_f32 v87, v90, v91
	global_store_dwordx4 v[100:101], v[84:87], off sc1
	s_nop 0
	s_nop 0
	v_or_b32_e32 v85, 48, v140
	v_fmamk_f32 v84, v203, 0x3a800000, v195
	v_rsq_f32_e32 v87, v84
	v_mad_i64_i32 v[84:85], s[14:15], v85, s53, v[120:121]
	v_lshl_add_u64 v[84:85], v[84:85], 0, v[122:123]
	v_mul_f32_e32 v86, 0xbfb8aa3b, v87
	v_pk_mul_f32 v[74:75], v[74:75], v[86:87] op_sel_hi:[1,0]
	v_pk_mul_f32 v[72:73], v[72:73], v[86:87] op_sel_hi:[1,0]
	v_pk_mul_f32 v[78:79], v[78:79], v[86:87] op_sel_hi:[1,0]
	v_pk_mul_f32 v[76:77], v[76:77], v[86:87] op_sel_hi:[1,0]
	v_exp_f32_e32 v72, v72
	v_exp_f32_e32 v74, v74
	v_exp_f32_e32 v75, v75
	v_exp_f32_e32 v73, v73
	v_exp_f32_e32 v76, v76
	v_exp_f32_e32 v77, v77
	v_exp_f32_e32 v78, v78
	v_exp_f32_e32 v79, v79
	v_pk_add_f32 v[74:75], v[74:75], 1.0 op_sel_hi:[1,0]
	v_pk_add_f32 v[72:73], v[72:73], 1.0 op_sel_hi:[1,0]
	v_pk_add_f32 v[76:77], v[76:77], 1.0 op_sel_hi:[1,0]
	v_pk_add_f32 v[78:79], v[78:79], 1.0 op_sel_hi:[1,0]
	v_rcp_f32_e32 v72, v72
	v_rcp_f32_e32 v73, v73
	v_rcp_f32_e32 v74, v74
	v_rcp_f32_e32 v75, v75
	v_rcp_f32_e32 v76, v76
	v_rcp_f32_e32 v77, v77
	v_rcp_f32_e32 v78, v78
	v_rcp_f32_e32 v79, v79
	v_mul_f32_e32 v88, v87, v87
	v_pk_mul_f32 v[72:73], v[88:89], v[72:73] op_sel_hi:[0,1]
	v_pk_mul_f32 v[74:75], v[88:89], v[74:75] op_sel_hi:[0,1]
	v_pk_mul_f32 v[76:77], v[88:89], v[76:77] op_sel_hi:[0,1]
	v_pk_mul_f32 v[78:79], v[88:89], v[78:79] op_sel_hi:[0,1]
	v_pk_mul_f32 v[74:75], v[70:71], v[74:75]
	v_pk_mul_f32 v[70:71], v[68:69], v[72:73]
	v_pk_mul_f32 v[78:79], v[82:83], v[78:79]
	v_pk_mul_f32 v[76:77], v[80:81], v[76:77]
	s_nop 0
	v_cvt_pk_bf16_f32 v68, v76, v77
	v_cvt_pk_bf16_f32 v69, v78, v79
	v_cvt_pk_bf16_f32 v70, v70, v71
	v_cvt_pk_bf16_f32 v71, v74, v75
	global_store_dwordx4 v[84:85], v[68:71], off sc1
	s_nop 0
	s_nop 0
	v_add_u32_e32 v69, 0x80, v140
	v_fmamk_f32 v68, v204, 0x3a800000, v195
	v_rsq_f32_e32 v71, v68
	v_mad_i64_i32 v[68:69], s[14:15], v69, s53, v[120:121]
	v_lshl_add_u64 v[68:69], v[68:69], 0, v[122:123]
	v_mul_f32_e32 v70, 0xbfb8aa3b, v71
	v_pk_mul_f32 v[58:59], v[58:59], v[70:71] op_sel_hi:[1,0]
	v_pk_mul_f32 v[56:57], v[56:57], v[70:71] op_sel_hi:[1,0]
	v_pk_mul_f32 v[62:63], v[62:63], v[70:71] op_sel_hi:[1,0]
	v_pk_mul_f32 v[60:61], v[60:61], v[70:71] op_sel_hi:[1,0]
	v_exp_f32_e32 v56, v56
	v_exp_f32_e32 v58, v58
	v_exp_f32_e32 v59, v59
	v_exp_f32_e32 v57, v57
	v_exp_f32_e32 v60, v60
	v_exp_f32_e32 v61, v61
	v_exp_f32_e32 v62, v62
	v_exp_f32_e32 v63, v63
	v_pk_add_f32 v[58:59], v[58:59], 1.0 op_sel_hi:[1,0]
	v_pk_add_f32 v[56:57], v[56:57], 1.0 op_sel_hi:[1,0]
	v_pk_add_f32 v[60:61], v[60:61], 1.0 op_sel_hi:[1,0]
	v_pk_add_f32 v[62:63], v[62:63], 1.0 op_sel_hi:[1,0]
	v_rcp_f32_e32 v56, v56
	v_rcp_f32_e32 v57, v57
	v_rcp_f32_e32 v58, v58
	v_rcp_f32_e32 v59, v59
	v_rcp_f32_e32 v60, v60
	v_rcp_f32_e32 v61, v61
	v_rcp_f32_e32 v62, v62
	v_rcp_f32_e32 v63, v63
	v_mul_f32_e32 v72, v71, v71
	v_pk_mul_f32 v[56:57], v[72:73], v[56:57] op_sel_hi:[0,1]
	v_pk_mul_f32 v[58:59], v[72:73], v[58:59] op_sel_hi:[0,1]
	v_pk_mul_f32 v[60:61], v[72:73], v[60:61] op_sel_hi:[0,1]
	v_pk_mul_f32 v[62:63], v[72:73], v[62:63] op_sel_hi:[0,1]
	v_pk_mul_f32 v[58:59], v[54:55], v[58:59]
	v_pk_mul_f32 v[54:55], v[52:53], v[56:57]
	v_pk_mul_f32 v[62:63], v[66:67], v[62:63]
	v_pk_mul_f32 v[60:61], v[64:65], v[60:61]
	s_nop 0
	v_cvt_pk_bf16_f32 v52, v60, v61
	v_cvt_pk_bf16_f32 v53, v62, v63
	v_cvt_pk_bf16_f32 v54, v54, v55
	v_cvt_pk_bf16_f32 v55, v58, v59
	global_store_dwordx4 v[68:69], v[52:55], off sc1
	s_nop 0
	s_nop 0
	v_add_u32_e32 v53, 0x90, v140
	v_fmamk_f32 v52, v205, 0x3a800000, v195
	v_rsq_f32_e32 v55, v52
	v_mad_i64_i32 v[52:53], s[14:15], v53, s53, v[120:121]
	v_lshl_add_u64 v[52:53], v[52:53], 0, v[122:123]
	v_mul_f32_e32 v54, 0xbfb8aa3b, v55
	v_pk_mul_f32 v[42:43], v[42:43], v[54:55] op_sel_hi:[1,0]
	v_pk_mul_f32 v[40:41], v[40:41], v[54:55] op_sel_hi:[1,0]
	v_pk_mul_f32 v[46:47], v[46:47], v[54:55] op_sel_hi:[1,0]
	v_pk_mul_f32 v[44:45], v[44:45], v[54:55] op_sel_hi:[1,0]
	v_exp_f32_e32 v40, v40
	v_exp_f32_e32 v42, v42
	v_exp_f32_e32 v43, v43
	v_exp_f32_e32 v41, v41
	v_exp_f32_e32 v44, v44
	v_exp_f32_e32 v45, v45
	v_exp_f32_e32 v46, v46
	v_exp_f32_e32 v47, v47
	v_pk_add_f32 v[42:43], v[42:43], 1.0 op_sel_hi:[1,0]
	v_pk_add_f32 v[40:41], v[40:41], 1.0 op_sel_hi:[1,0]
	v_pk_add_f32 v[44:45], v[44:45], 1.0 op_sel_hi:[1,0]
	v_pk_add_f32 v[46:47], v[46:47], 1.0 op_sel_hi:[1,0]
	v_rcp_f32_e32 v40, v40
	v_rcp_f32_e32 v41, v41
	v_rcp_f32_e32 v42, v42
	v_rcp_f32_e32 v43, v43
	v_rcp_f32_e32 v44, v44
	v_rcp_f32_e32 v45, v45
	v_rcp_f32_e32 v46, v46
	v_rcp_f32_e32 v47, v47
	v_mul_f32_e32 v56, v55, v55
	v_pk_mul_f32 v[40:41], v[56:57], v[40:41] op_sel_hi:[0,1]
	v_pk_mul_f32 v[42:43], v[56:57], v[42:43] op_sel_hi:[0,1]
	v_pk_mul_f32 v[44:45], v[56:57], v[44:45] op_sel_hi:[0,1]
	v_pk_mul_f32 v[46:47], v[56:57], v[46:47] op_sel_hi:[0,1]
	v_pk_mul_f32 v[42:43], v[38:39], v[42:43]
	v_pk_mul_f32 v[38:39], v[36:37], v[40:41]
	v_pk_mul_f32 v[46:47], v[50:51], v[46:47]
	v_pk_mul_f32 v[44:45], v[48:49], v[44:45]
	s_nop 0
	v_cvt_pk_bf16_f32 v36, v44, v45
	v_cvt_pk_bf16_f32 v37, v46, v47
	v_cvt_pk_bf16_f32 v38, v38, v39
	v_cvt_pk_bf16_f32 v39, v42, v43
	global_store_dwordx4 v[52:53], v[36:39], off sc1
	s_nop 0
	s_nop 0
	v_add_u32_e32 v37, 0xa0, v140
	v_fmamk_f32 v36, v206, 0x3a800000, v195
	v_rsq_f32_e32 v39, v36
	v_mad_i64_i32 v[36:37], s[14:15], v37, s53, v[120:121]
	v_lshl_add_u64 v[36:37], v[36:37], 0, v[122:123]
	v_mul_f32_e32 v38, 0xbfb8aa3b, v39
	v_pk_mul_f32 v[26:27], v[26:27], v[38:39] op_sel_hi:[1,0]
	v_pk_mul_f32 v[24:25], v[24:25], v[38:39] op_sel_hi:[1,0]
	v_pk_mul_f32 v[30:31], v[30:31], v[38:39] op_sel_hi:[1,0]
	v_pk_mul_f32 v[28:29], v[28:29], v[38:39] op_sel_hi:[1,0]
	v_exp_f32_e32 v24, v24
	v_exp_f32_e32 v26, v26
	v_exp_f32_e32 v27, v27
	v_exp_f32_e32 v25, v25
	v_exp_f32_e32 v28, v28
	v_exp_f32_e32 v29, v29
	v_exp_f32_e32 v30, v30
	v_exp_f32_e32 v31, v31
	v_pk_add_f32 v[26:27], v[26:27], 1.0 op_sel_hi:[1,0]
	v_pk_add_f32 v[24:25], v[24:25], 1.0 op_sel_hi:[1,0]
	v_pk_add_f32 v[28:29], v[28:29], 1.0 op_sel_hi:[1,0]
	v_pk_add_f32 v[30:31], v[30:31], 1.0 op_sel_hi:[1,0]
	v_rcp_f32_e32 v24, v24
	v_rcp_f32_e32 v25, v25
	v_rcp_f32_e32 v26, v26
	v_rcp_f32_e32 v27, v27
	v_rcp_f32_e32 v28, v28
	v_rcp_f32_e32 v29, v29
	v_rcp_f32_e32 v30, v30
	v_rcp_f32_e32 v31, v31
	v_mul_f32_e32 v40, v39, v39
	v_pk_mul_f32 v[24:25], v[40:41], v[24:25] op_sel_hi:[0,1]
	v_pk_mul_f32 v[26:27], v[40:41], v[26:27] op_sel_hi:[0,1]
	v_pk_mul_f32 v[28:29], v[40:41], v[28:29] op_sel_hi:[0,1]
	v_pk_mul_f32 v[30:31], v[40:41], v[30:31] op_sel_hi:[0,1]
	v_pk_mul_f32 v[26:27], v[22:23], v[26:27]
	v_pk_mul_f32 v[22:23], v[20:21], v[24:25]
	v_pk_mul_f32 v[30:31], v[34:35], v[30:31]
	v_pk_mul_f32 v[28:29], v[32:33], v[28:29]
	s_nop 0
	v_cvt_pk_bf16_f32 v20, v28, v29
	v_cvt_pk_bf16_f32 v21, v30, v31
	v_cvt_pk_bf16_f32 v22, v22, v23
	v_cvt_pk_bf16_f32 v23, v26, v27
	global_store_dwordx4 v[36:37], v[20:23], off sc1
	s_nop 0
	s_nop 0
	v_add_u32_e32 v21, 0xb0, v140
	v_fmamk_f32 v20, v207, 0x3a800000, v195
	v_rsq_f32_e32 v23, v20
	v_mad_i64_i32 v[20:21], s[14:15], v21, s53, v[120:121]
	v_lshl_add_u64 v[20:21], v[20:21], 0, v[122:123]
	v_mul_f32_e32 v22, 0xbfb8aa3b, v23
	v_pk_mul_f32 v[6:7], v[6:7], v[22:23] op_sel_hi:[1,0]
	v_pk_mul_f32 v[4:5], v[4:5], v[22:23] op_sel_hi:[1,0]
	v_pk_mul_f32 v[14:15], v[14:15], v[22:23] op_sel_hi:[1,0]
	v_pk_mul_f32 v[12:13], v[12:13], v[22:23] op_sel_hi:[1,0]
	v_exp_f32_e32 v4, v4
	v_exp_f32_e32 v6, v6
	v_exp_f32_e32 v7, v7
	v_exp_f32_e32 v5, v5
	v_exp_f32_e32 v12, v12
	v_exp_f32_e32 v13, v13
	v_exp_f32_e32 v14, v14
	v_exp_f32_e32 v15, v15
	v_pk_add_f32 v[6:7], v[6:7], 1.0 op_sel_hi:[1,0]
	v_pk_add_f32 v[4:5], v[4:5], 1.0 op_sel_hi:[1,0]
	v_pk_add_f32 v[12:13], v[12:13], 1.0 op_sel_hi:[1,0]
	v_pk_add_f32 v[14:15], v[14:15], 1.0 op_sel_hi:[1,0]
	v_rcp_f32_e32 v4, v4
	v_rcp_f32_e32 v5, v5
	v_rcp_f32_e32 v6, v6
	v_rcp_f32_e32 v7, v7
	v_rcp_f32_e32 v12, v12
	v_rcp_f32_e32 v13, v13
	v_rcp_f32_e32 v14, v14
	v_rcp_f32_e32 v15, v15
	v_mul_f32_e32 v24, v23, v23
	v_pk_mul_f32 v[4:5], v[24:25], v[4:5] op_sel_hi:[0,1]
	v_pk_mul_f32 v[6:7], v[24:25], v[6:7] op_sel_hi:[0,1]
	v_pk_mul_f32 v[12:13], v[24:25], v[12:13] op_sel_hi:[0,1]
	v_pk_mul_f32 v[14:15], v[24:25], v[14:15] op_sel_hi:[0,1]
	v_pk_mul_f32 v[10:11], v[10:11], v[6:7]
	v_pk_mul_f32 v[6:7], v[8:9], v[4:5]
	v_pk_mul_f32 v[14:15], v[18:19], v[14:15]
	v_pk_mul_f32 v[12:13], v[16:17], v[12:13]
	s_nop 0
	v_cvt_pk_bf16_f32 v4, v12, v13
	v_cvt_pk_bf16_f32 v5, v14, v15
	v_cvt_pk_bf16_f32 v6, v6, v7
	v_cvt_pk_bf16_f32 v7, v10, v11
	global_store_dwordx4 v[20:21], v[4:7], off sc1
	s_cbranch_vccnz .LBB0_956
	s_andn2_b64 vcc, exec, s[4:5]
	s_cbranch_vccnz .LBB0_955
	s_barrier
	s_branch .LBB0_955

.LBB0_1047:
	v_lshl_add_u32 v154, s54, 8, v146
	v_lshl_or_b32 v145, s51, 8, v148
	v_lshl_add_u32 v144, v154, 10, v145
	v_lshlrev_b32_e32 v144, 1, v144
	v_mov_b32_e32 v145, v144
	v_lshlrev_b32_e32 v154, 2, v154
	global_load_dwordx4 v[140:143], v144, s[6:7]
	global_load_dwordx4 v[150:153], v144, s[6:7] offset:256
	v_add_u32_e32 v144, 0x8000, v144
	global_load_dwordx4 v[172:175], v144, s[6:7]
	global_load_dwordx4 v[176:179], v144, s[6:7] offset:256
	v_add_u32_e32 v144, 0x8000, v144
	global_load_dwordx4 v[180:183], v144, s[6:7]
	global_load_dwordx4 v[184:187], v144, s[6:7] offset:256
	v_add_u32_e32 v144, 0x8000, v144
	global_load_dwordx4 v[188:191], v144, s[6:7]
	global_load_dwordx4 v[200:203], v144, s[6:7] offset:256
	v_add_u32_e32 v144, 0x28000, v144
	global_load_dwordx4 v[204:207], v144, s[6:7]
	global_load_dwordx4 v[208:211], v144, s[6:7] offset:256
	v_add_u32_e32 v144, 0x8000, v144
	global_load_dwordx4 v[212:215], v144, s[6:7]
	global_load_dwordx4 v[216:219], v144, s[6:7] offset:256
	v_add_u32_e32 v144, 0x8000, v144
	global_load_dwordx4 v[220:223], v144, s[6:7]
	global_load_dwordx4 v[224:227], v144, s[6:7] offset:256
	v_add_u32_e32 v144, 0x8000, v144
	global_load_dwordx4 v[228:231], v144, s[6:7]
	global_load_dwordx4 v[232:235], v144, s[6:7] offset:256
	v_xor_b32_e32 v155, 16, v197
	v_xor_b32_e32 v192, 32, v197
	v_lshlrev_b32_e32 v155, 2, v155
	v_lshlrev_b32_e32 v192, 2, v192
	s_waitcnt vmcnt(14)
	v_lshlrev_b32_e32 v236, 16, v140
	v_and_b32_e32 v237, 0xffff0000, v140
	v_lshlrev_b32_e32 v238, 16, v141
	v_and_b32_e32 v239, 0xffff0000, v141
	v_lshlrev_b32_e32 v140, 16, v142
	v_and_b32_e32 v141, 0xffff0000, v142
	v_lshlrev_b32_e32 v142, 16, v143
	v_and_b32_e32 v143, 0xffff0000, v143
	v_pk_add_f32 v[128:129], v[128:129], v[236:237]
	v_pk_add_f32 v[130:131], v[130:131], v[238:239]
	v_pk_add_f32 v[124:125], v[124:125], v[140:141]
	v_pk_add_f32 v[126:127], v[126:127], v[142:143]
	v_cvt_pk_bf16_f32 v140, v128, v129
	v_cvt_pk_bf16_f32 v141, v130, v131
	v_cvt_pk_bf16_f32 v142, v124, v125
	v_cvt_pk_bf16_f32 v143, v126, v127
	global_store_dwordx4 v145, v[140:143], s[6:7] sc1
	v_pk_mul_f32 v[128:129], v[128:129], v[128:129]
	v_pk_mul_f32 v[130:131], v[130:131], v[130:131]
	v_pk_fma_f32 v[128:129], v[124:125], v[124:125], v[128:129]
	v_pk_fma_f32 v[130:131], v[126:127], v[126:127], v[130:131]
	v_lshlrev_b32_e32 v236, 16, v150
	v_and_b32_e32 v237, 0xffff0000, v150
	v_lshlrev_b32_e32 v238, 16, v151
	v_and_b32_e32 v239, 0xffff0000, v151
	v_lshlrev_b32_e32 v150, 16, v152
	v_and_b32_e32 v151, 0xffff0000, v152
	v_lshlrev_b32_e32 v152, 16, v153
	v_and_b32_e32 v153, 0xffff0000, v153
	v_pk_add_f32 v[120:121], v[120:121], v[236:237]
	v_pk_add_f32 v[122:123], v[122:123], v[238:239]
	v_pk_add_f32 v[116:117], v[116:117], v[150:151]
	v_pk_add_f32 v[118:119], v[118:119], v[152:153]
	v_cvt_pk_bf16_f32 v150, v120, v121
	v_cvt_pk_bf16_f32 v151, v122, v123
	v_cvt_pk_bf16_f32 v152, v116, v117
	v_cvt_pk_bf16_f32 v153, v118, v119
	global_store_dwordx4 v145, v[150:153], s[6:7] offset:256 sc1
	v_pk_fma_f32 v[128:129], v[120:121], v[120:121], v[128:129]
	v_pk_fma_f32 v[130:131], v[122:123], v[122:123], v[130:131]
	v_pk_fma_f32 v[128:129], v[116:117], v[116:117], v[128:129]
	v_pk_fma_f32 v[130:131], v[118:119], v[118:119], v[130:131]
	v_add_u32_e32 v145, 0x8000, v145
	v_add_f32_e32 v128, v128, v129
	v_add_f32_e32 v130, v130, v131
	v_add_f32_e32 v128, v128, v130
	s_waitcnt vmcnt(14)
	v_lshlrev_b32_e32 v236, 16, v172
	v_and_b32_e32 v237, 0xffff0000, v172
	v_lshlrev_b32_e32 v238, 16, v173
	v_and_b32_e32 v239, 0xffff0000, v173
	v_lshlrev_b32_e32 v172, 16, v174
	v_and_b32_e32 v173, 0xffff0000, v174
	v_lshlrev_b32_e32 v174, 16, v175
	v_and_b32_e32 v175, 0xffff0000, v175
	v_pk_add_f32 v[112:113], v[112:113], v[236:237]
	v_pk_add_f32 v[114:115], v[114:115], v[238:239]
	v_pk_add_f32 v[108:109], v[108:109], v[172:173]
	v_pk_add_f32 v[110:111], v[110:111], v[174:175]
	v_cvt_pk_bf16_f32 v172, v112, v113
	v_cvt_pk_bf16_f32 v173, v114, v115
	v_cvt_pk_bf16_f32 v174, v108, v109
	v_cvt_pk_bf16_f32 v175, v110, v111
	global_store_dwordx4 v145, v[172:175], s[6:7] sc1
	v_pk_mul_f32 v[112:113], v[112:113], v[112:113]
	v_pk_mul_f32 v[114:115], v[114:115], v[114:115]
	v_pk_fma_f32 v[112:113], v[108:109], v[108:109], v[112:113]
	v_pk_fma_f32 v[114:115], v[110:111], v[110:111], v[114:115]
	v_lshlrev_b32_e32 v236, 16, v176
	v_and_b32_e32 v237, 0xffff0000, v176
	v_lshlrev_b32_e32 v238, 16, v177
	v_and_b32_e32 v239, 0xffff0000, v177
	v_lshlrev_b32_e32 v176, 16, v178
	v_and_b32_e32 v177, 0xffff0000, v178
	v_lshlrev_b32_e32 v178, 16, v179
	v_and_b32_e32 v179, 0xffff0000, v179
	v_pk_add_f32 v[104:105], v[104:105], v[236:237]
	v_pk_add_f32 v[106:107], v[106:107], v[238:239]
	v_pk_add_f32 v[100:101], v[100:101], v[176:177]
	v_pk_add_f32 v[102:103], v[102:103], v[178:179]
	v_cvt_pk_bf16_f32 v176, v104, v105
	v_cvt_pk_bf16_f32 v177, v106, v107
	v_cvt_pk_bf16_f32 v178, v100, v101
	v_cvt_pk_bf16_f32 v179, v102, v103
	global_store_dwordx4 v145, v[176:179], s[6:7] offset:256 sc1
	v_pk_fma_f32 v[112:113], v[104:105], v[104:105], v[112:113]
	v_pk_fma_f32 v[114:115], v[106:107], v[106:107], v[114:115]
	v_pk_fma_f32 v[112:113], v[100:101], v[100:101], v[112:113]
	v_pk_fma_f32 v[114:115], v[102:103], v[102:103], v[114:115]
	v_add_u32_e32 v145, 0x8000, v145
	v_add_f32_e32 v112, v112, v113
	v_add_f32_e32 v114, v114, v115
	v_add_f32_e32 v112, v112, v114
	s_waitcnt vmcnt(14)
	v_lshlrev_b32_e32 v236, 16, v180
	v_and_b32_e32 v237, 0xffff0000, v180
	v_lshlrev_b32_e32 v238, 16, v181
	v_and_b32_e32 v239, 0xffff0000, v181
	v_lshlrev_b32_e32 v180, 16, v182
	v_and_b32_e32 v181, 0xffff0000, v182
	v_lshlrev_b32_e32 v182, 16, v183
	v_and_b32_e32 v183, 0xffff0000, v183
	v_pk_add_f32 v[96:97], v[96:97], v[236:237]
	v_pk_add_f32 v[98:99], v[98:99], v[238:239]
	v_pk_add_f32 v[92:93], v[92:93], v[180:181]
	v_pk_add_f32 v[94:95], v[94:95], v[182:183]
	v_cvt_pk_bf16_f32 v180, v96, v97
	v_cvt_pk_bf16_f32 v181, v98, v99
	v_cvt_pk_bf16_f32 v182, v92, v93
	v_cvt_pk_bf16_f32 v183, v94, v95
	global_store_dwordx4 v145, v[180:183], s[6:7] sc1
	v_pk_mul_f32 v[96:97], v[96:97], v[96:97]
	v_pk_mul_f32 v[98:99], v[98:99], v[98:99]
	v_pk_fma_f32 v[96:97], v[92:93], v[92:93], v[96:97]
	v_pk_fma_f32 v[98:99], v[94:95], v[94:95], v[98:99]
	v_lshlrev_b32_e32 v236, 16, v184
	v_and_b32_e32 v237, 0xffff0000, v184
	v_lshlrev_b32_e32 v238, 16, v185
	v_and_b32_e32 v239, 0xffff0000, v185
	v_lshlrev_b32_e32 v184, 16, v186
	v_and_b32_e32 v185, 0xffff0000, v186
	v_lshlrev_b32_e32 v186, 16, v187
	v_and_b32_e32 v187, 0xffff0000, v187
	v_pk_add_f32 v[88:89], v[88:89], v[236:237]
	v_pk_add_f32 v[90:91], v[90:91], v[238:239]
	v_pk_add_f32 v[84:85], v[84:85], v[184:185]
	v_pk_add_f32 v[86:87], v[86:87], v[186:187]
	v_cvt_pk_bf16_f32 v184, v88, v89
	v_cvt_pk_bf16_f32 v185, v90, v91
	v_cvt_pk_bf16_f32 v186, v84, v85
	v_cvt_pk_bf16_f32 v187, v86, v87
	global_store_dwordx4 v145, v[184:187], s[6:7] offset:256 sc1
	v_pk_fma_f32 v[96:97], v[88:89], v[88:89], v[96:97]
	v_pk_fma_f32 v[98:99], v[90:91], v[90:91], v[98:99]
	v_pk_fma_f32 v[96:97], v[84:85], v[84:85], v[96:97]
	v_pk_fma_f32 v[98:99], v[86:87], v[86:87], v[98:99]
	v_add_u32_e32 v145, 0x8000, v145
	v_add_f32_e32 v96, v96, v97
	v_add_f32_e32 v98, v98, v99
	v_add_f32_e32 v96, v96, v98
	s_waitcnt vmcnt(14)
	v_lshlrev_b32_e32 v236, 16, v188
	v_and_b32_e32 v237, 0xffff0000, v188
	v_lshlrev_b32_e32 v238, 16, v189
	v_and_b32_e32 v239, 0xffff0000, v189
	v_lshlrev_b32_e32 v188, 16, v190
	v_and_b32_e32 v189, 0xffff0000, v190
	v_lshlrev_b32_e32 v190, 16, v191
	v_and_b32_e32 v191, 0xffff0000, v191
	v_pk_add_f32 v[80:81], v[80:81], v[236:237]
	v_pk_add_f32 v[82:83], v[82:83], v[238:239]
	v_pk_add_f32 v[76:77], v[76:77], v[188:189]
	v_pk_add_f32 v[78:79], v[78:79], v[190:191]
	v_cvt_pk_bf16_f32 v188, v80, v81
	v_cvt_pk_bf16_f32 v189, v82, v83
	v_cvt_pk_bf16_f32 v190, v76, v77
	v_cvt_pk_bf16_f32 v191, v78, v79
	global_store_dwordx4 v145, v[188:191], s[6:7] sc1
	v_pk_mul_f32 v[80:81], v[80:81], v[80:81]
	v_pk_mul_f32 v[82:83], v[82:83], v[82:83]
	v_pk_fma_f32 v[80:81], v[76:77], v[76:77], v[80:81]
	v_pk_fma_f32 v[82:83], v[78:79], v[78:79], v[82:83]
	v_lshlrev_b32_e32 v236, 16, v200
	v_and_b32_e32 v237, 0xffff0000, v200
	v_lshlrev_b32_e32 v238, 16, v201
	v_and_b32_e32 v239, 0xffff0000, v201
	v_lshlrev_b32_e32 v200, 16, v202
	v_and_b32_e32 v201, 0xffff0000, v202
	v_lshlrev_b32_e32 v202, 16, v203
	v_and_b32_e32 v203, 0xffff0000, v203
	v_pk_add_f32 v[72:73], v[72:73], v[236:237]
	v_pk_add_f32 v[74:75], v[74:75], v[238:239]
	v_pk_add_f32 v[68:69], v[68:69], v[200:201]
	v_pk_add_f32 v[70:71], v[70:71], v[202:203]
	v_cvt_pk_bf16_f32 v200, v72, v73
	v_cvt_pk_bf16_f32 v201, v74, v75
	v_cvt_pk_bf16_f32 v202, v68, v69
	v_cvt_pk_bf16_f32 v203, v70, v71
	global_store_dwordx4 v145, v[200:203], s[6:7] offset:256 sc1
	v_pk_fma_f32 v[80:81], v[72:73], v[72:73], v[80:81]
	v_pk_fma_f32 v[82:83], v[74:75], v[74:75], v[82:83]
	v_pk_fma_f32 v[80:81], v[68:69], v[68:69], v[80:81]
	v_pk_fma_f32 v[82:83], v[70:71], v[70:71], v[82:83]
	v_add_u32_e32 v145, 0x28000, v145
	v_add_f32_e32 v80, v80, v81
	v_add_f32_e32 v82, v82, v83
	v_add_f32_e32 v80, v80, v82
	s_waitcnt vmcnt(14)
	v_lshlrev_b32_e32 v236, 16, v204
	v_and_b32_e32 v237, 0xffff0000, v204
	v_lshlrev_b32_e32 v238, 16, v205
	v_and_b32_e32 v239, 0xffff0000, v205
	v_lshlrev_b32_e32 v204, 16, v206
	v_and_b32_e32 v205, 0xffff0000, v206
	v_lshlrev_b32_e32 v206, 16, v207
	v_and_b32_e32 v207, 0xffff0000, v207
	v_pk_add_f32 v[64:65], v[64:65], v[236:237]
	v_pk_add_f32 v[66:67], v[66:67], v[238:239]
	v_pk_add_f32 v[60:61], v[60:61], v[204:205]
	v_pk_add_f32 v[62:63], v[62:63], v[206:207]
	v_cvt_pk_bf16_f32 v204, v64, v65
	v_cvt_pk_bf16_f32 v205, v66, v67
	v_cvt_pk_bf16_f32 v206, v60, v61
	v_cvt_pk_bf16_f32 v207, v62, v63
	global_store_dwordx4 v145, v[204:207], s[6:7] sc1
	v_pk_mul_f32 v[64:65], v[64:65], v[64:65]
	v_pk_mul_f32 v[66:67], v[66:67], v[66:67]
	v_pk_fma_f32 v[64:65], v[60:61], v[60:61], v[64:65]
	v_pk_fma_f32 v[66:67], v[62:63], v[62:63], v[66:67]
	v_lshlrev_b32_e32 v236, 16, v208
	v_and_b32_e32 v237, 0xffff0000, v208
	v_lshlrev_b32_e32 v238, 16, v209
	v_and_b32_e32 v239, 0xffff0000, v209
	v_lshlrev_b32_e32 v208, 16, v210
	v_and_b32_e32 v209, 0xffff0000, v210
	v_lshlrev_b32_e32 v210, 16, v211
	v_and_b32_e32 v211, 0xffff0000, v211
	v_pk_add_f32 v[56:57], v[56:57], v[236:237]
	v_pk_add_f32 v[58:59], v[58:59], v[238:239]
	v_pk_add_f32 v[52:53], v[52:53], v[208:209]
	v_pk_add_f32 v[54:55], v[54:55], v[210:211]
	v_cvt_pk_bf16_f32 v208, v56, v57
	v_cvt_pk_bf16_f32 v209, v58, v59
	v_cvt_pk_bf16_f32 v210, v52, v53
	v_cvt_pk_bf16_f32 v211, v54, v55
	global_store_dwordx4 v145, v[208:211], s[6:7] offset:256 sc1
	v_pk_fma_f32 v[64:65], v[56:57], v[56:57], v[64:65]
	v_pk_fma_f32 v[66:67], v[58:59], v[58:59], v[66:67]
	v_pk_fma_f32 v[64:65], v[52:53], v[52:53], v[64:65]
	v_pk_fma_f32 v[66:67], v[54:55], v[54:55], v[66:67]
	v_add_u32_e32 v145, 0x8000, v145
	v_add_f32_e32 v64, v64, v65
	v_add_f32_e32 v66, v66, v67
	v_add_f32_e32 v64, v64, v66
	s_waitcnt vmcnt(14)
	v_lshlrev_b32_e32 v236, 16, v212
	v_and_b32_e32 v237, 0xffff0000, v212
	v_lshlrev_b32_e32 v238, 16, v213
	v_and_b32_e32 v239, 0xffff0000, v213
	v_lshlrev_b32_e32 v212, 16, v214
	v_and_b32_e32 v213, 0xffff0000, v214
	v_lshlrev_b32_e32 v214, 16, v215
	v_and_b32_e32 v215, 0xffff0000, v215
	v_pk_add_f32 v[48:49], v[48:49], v[236:237]
	v_pk_add_f32 v[50:51], v[50:51], v[238:239]
	v_pk_add_f32 v[44:45], v[44:45], v[212:213]
	v_pk_add_f32 v[46:47], v[46:47], v[214:215]
	v_cvt_pk_bf16_f32 v212, v48, v49
	v_cvt_pk_bf16_f32 v213, v50, v51
	v_cvt_pk_bf16_f32 v214, v44, v45
	v_cvt_pk_bf16_f32 v215, v46, v47
	global_store_dwordx4 v145, v[212:215], s[6:7] sc1
	v_pk_mul_f32 v[48:49], v[48:49], v[48:49]
	v_pk_mul_f32 v[50:51], v[50:51], v[50:51]
	v_pk_fma_f32 v[48:49], v[44:45], v[44:45], v[48:49]
	v_pk_fma_f32 v[50:51], v[46:47], v[46:47], v[50:51]
	v_lshlrev_b32_e32 v236, 16, v216
	v_and_b32_e32 v237, 0xffff0000, v216
	v_lshlrev_b32_e32 v238, 16, v217
	v_and_b32_e32 v239, 0xffff0000, v217
	v_lshlrev_b32_e32 v216, 16, v218
	v_and_b32_e32 v217, 0xffff0000, v218
	v_lshlrev_b32_e32 v218, 16, v219
	v_and_b32_e32 v219, 0xffff0000, v219
	v_pk_add_f32 v[40:41], v[40:41], v[236:237]
	v_pk_add_f32 v[42:43], v[42:43], v[238:239]
	v_pk_add_f32 v[36:37], v[36:37], v[216:217]
	v_pk_add_f32 v[38:39], v[38:39], v[218:219]
	v_cvt_pk_bf16_f32 v216, v40, v41
	v_cvt_pk_bf16_f32 v217, v42, v43
	v_cvt_pk_bf16_f32 v218, v36, v37
	v_cvt_pk_bf16_f32 v219, v38, v39
	global_store_dwordx4 v145, v[216:219], s[6:7] offset:256 sc1
	v_pk_fma_f32 v[48:49], v[40:41], v[40:41], v[48:49]
	v_pk_fma_f32 v[50:51], v[42:43], v[42:43], v[50:51]
	v_pk_fma_f32 v[48:49], v[36:37], v[36:37], v[48:49]
	v_pk_fma_f32 v[50:51], v[38:39], v[38:39], v[50:51]
	v_add_u32_e32 v145, 0x8000, v145
	v_add_f32_e32 v48, v48, v49
	v_add_f32_e32 v50, v50, v51
	v_add_f32_e32 v48, v48, v50
	s_waitcnt vmcnt(14)
	v_lshlrev_b32_e32 v236, 16, v220
	v_and_b32_e32 v237, 0xffff0000, v220
	v_lshlrev_b32_e32 v238, 16, v221
	v_and_b32_e32 v239, 0xffff0000, v221
	v_lshlrev_b32_e32 v220, 16, v222
	v_and_b32_e32 v221, 0xffff0000, v222
	v_lshlrev_b32_e32 v222, 16, v223
	v_and_b32_e32 v223, 0xffff0000, v223
	v_pk_add_f32 v[32:33], v[32:33], v[236:237]
	v_pk_add_f32 v[34:35], v[34:35], v[238:239]
	v_pk_add_f32 v[28:29], v[28:29], v[220:221]
	v_pk_add_f32 v[30:31], v[30:31], v[222:223]
	v_cvt_pk_bf16_f32 v220, v32, v33
	v_cvt_pk_bf16_f32 v221, v34, v35
	v_cvt_pk_bf16_f32 v222, v28, v29
	v_cvt_pk_bf16_f32 v223, v30, v31
	global_store_dwordx4 v145, v[220:223], s[6:7] sc1
	v_pk_mul_f32 v[32:33], v[32:33], v[32:33]
	v_pk_mul_f32 v[34:35], v[34:35], v[34:35]
	v_pk_fma_f32 v[32:33], v[28:29], v[28:29], v[32:33]
	v_pk_fma_f32 v[34:35], v[30:31], v[30:31], v[34:35]
	v_lshlrev_b32_e32 v236, 16, v224
	v_and_b32_e32 v237, 0xffff0000, v224
	v_lshlrev_b32_e32 v238, 16, v225
	v_and_b32_e32 v239, 0xffff0000, v225
	v_lshlrev_b32_e32 v224, 16, v226
	v_and_b32_e32 v225, 0xffff0000, v226
	v_lshlrev_b32_e32 v226, 16, v227
	v_and_b32_e32 v227, 0xffff0000, v227
	v_pk_add_f32 v[24:25], v[24:25], v[236:237]
	v_pk_add_f32 v[26:27], v[26:27], v[238:239]
	v_pk_add_f32 v[20:21], v[20:21], v[224:225]
	v_pk_add_f32 v[22:23], v[22:23], v[226:227]
	v_cvt_pk_bf16_f32 v224, v24, v25
	v_cvt_pk_bf16_f32 v225, v26, v27
	v_cvt_pk_bf16_f32 v226, v20, v21
	v_cvt_pk_bf16_f32 v227, v22, v23
	global_store_dwordx4 v145, v[224:227], s[6:7] offset:256 sc1
	v_pk_fma_f32 v[32:33], v[24:25], v[24:25], v[32:33]
	v_pk_fma_f32 v[34:35], v[26:27], v[26:27], v[34:35]
	v_pk_fma_f32 v[32:33], v[20:21], v[20:21], v[32:33]
	v_pk_fma_f32 v[34:35], v[22:23], v[22:23], v[34:35]
	v_add_u32_e32 v145, 0x8000, v145
	v_add_f32_e32 v32, v32, v33
	v_add_f32_e32 v34, v34, v35
	v_add_f32_e32 v32, v32, v34
	s_waitcnt vmcnt(14)
	v_lshlrev_b32_e32 v236, 16, v228
	v_and_b32_e32 v237, 0xffff0000, v228
	v_lshlrev_b32_e32 v238, 16, v229
	v_and_b32_e32 v239, 0xffff0000, v229
	v_lshlrev_b32_e32 v228, 16, v230
	v_and_b32_e32 v229, 0xffff0000, v230
	v_lshlrev_b32_e32 v230, 16, v231
	v_and_b32_e32 v231, 0xffff0000, v231
	v_pk_add_f32 v[16:17], v[16:17], v[236:237]
	v_pk_add_f32 v[18:19], v[18:19], v[238:239]
	v_pk_add_f32 v[12:13], v[12:13], v[228:229]
	v_pk_add_f32 v[14:15], v[14:15], v[230:231]
	v_cvt_pk_bf16_f32 v228, v16, v17
	v_cvt_pk_bf16_f32 v229, v18, v19
	v_cvt_pk_bf16_f32 v230, v12, v13
	v_cvt_pk_bf16_f32 v231, v14, v15
	global_store_dwordx4 v145, v[228:231], s[6:7] sc1
	v_pk_mul_f32 v[16:17], v[16:17], v[16:17]
	v_pk_mul_f32 v[18:19], v[18:19], v[18:19]
	v_pk_fma_f32 v[16:17], v[12:13], v[12:13], v[16:17]
	v_pk_fma_f32 v[18:19], v[14:15], v[14:15], v[18:19]
	v_lshlrev_b32_e32 v236, 16, v232
	v_and_b32_e32 v237, 0xffff0000, v232
	v_lshlrev_b32_e32 v238, 16, v233
	v_and_b32_e32 v239, 0xffff0000, v233
	v_lshlrev_b32_e32 v232, 16, v234
	v_and_b32_e32 v233, 0xffff0000, v234
	v_lshlrev_b32_e32 v234, 16, v235
	v_and_b32_e32 v235, 0xffff0000, v235
	v_pk_add_f32 v[8:9], v[8:9], v[236:237]
	v_pk_add_f32 v[10:11], v[10:11], v[238:239]
	v_pk_add_f32 v[4:5], v[4:5], v[232:233]
	v_pk_add_f32 v[6:7], v[6:7], v[234:235]
	v_cvt_pk_bf16_f32 v232, v8, v9
	v_cvt_pk_bf16_f32 v233, v10, v11
	v_cvt_pk_bf16_f32 v234, v4, v5
	v_cvt_pk_bf16_f32 v235, v6, v7
	global_store_dwordx4 v145, v[232:235], s[6:7] offset:256 sc1
	v_pk_fma_f32 v[16:17], v[8:9], v[8:9], v[16:17]
	v_pk_fma_f32 v[18:19], v[10:11], v[10:11], v[18:19]
	v_pk_fma_f32 v[16:17], v[4:5], v[4:5], v[16:17]
	v_pk_fma_f32 v[18:19], v[6:7], v[6:7], v[18:19]
	v_add_f32_e32 v16, v16, v17
	v_add_f32_e32 v18, v18, v19
	v_add_f32_e32 v16, v16, v18
	ds_bpermute_b32 v129, v155, v128
	ds_bpermute_b32 v113, v155, v112
	ds_bpermute_b32 v97, v155, v96
	ds_bpermute_b32 v81, v155, v80
	ds_bpermute_b32 v65, v155, v64
	ds_bpermute_b32 v49, v155, v48
	ds_bpermute_b32 v33, v155, v32
	ds_bpermute_b32 v17, v155, v16
	s_waitcnt lgkmcnt(0)
	v_add_f32_e32 v128, v128, v129
	v_add_f32_e32 v112, v112, v113
	v_add_f32_e32 v96, v96, v97
	v_add_f32_e32 v80, v80, v81
	v_add_f32_e32 v64, v64, v65
	v_add_f32_e32 v48, v48, v49
	v_add_f32_e32 v32, v32, v33
	v_add_f32_e32 v16, v16, v17
	ds_bpermute_b32 v129, v192, v128
	ds_bpermute_b32 v113, v192, v112
	ds_bpermute_b32 v97, v192, v96
	ds_bpermute_b32 v81, v192, v80
	ds_bpermute_b32 v65, v192, v64
	ds_bpermute_b32 v49, v192, v48
	ds_bpermute_b32 v33, v192, v32
	ds_bpermute_b32 v17, v192, v16
	s_waitcnt lgkmcnt(0)
	s_and_saveexec_b64 s[14:15], s[0:1]
	v_add_f32_e32 v128, v128, v129
	v_add_f32_e32 v112, v112, v113
	v_add_f32_e32 v96, v96, v97
	v_add_f32_e32 v80, v80, v81
	v_add_f32_e32 v64, v64, v65
	v_add_f32_e32 v48, v48, v49
	v_add_f32_e32 v32, v32, v33
	v_add_f32_e32 v16, v16, v17
	global_atomic_add_f32 v154, v128, s[8:9]
	global_atomic_add_f32 v154, v112, s[8:9] offset:64
	global_atomic_add_f32 v154, v96, s[8:9] offset:128
	global_atomic_add_f32 v154, v80, s[8:9] offset:192
	global_atomic_add_f32 v154, v64, s[8:9] offset:512
	global_atomic_add_f32 v154, v48, s[8:9] offset:576
	global_atomic_add_f32 v154, v32, s[8:9] offset:640
	global_atomic_add_f32 v154, v16, s[8:9] offset:704
